# RWKV producer: next-chunk second-half operand prefetch issued with the first half (fresh registers), drops 8 copies; hand scanner (burst LDS)
# speedup vs baseline: 1.0045x; 1.0045x over previous
.Lstag_done:
	s_and_b32 s1, s0, 1
	s_lshl_b32 s31, s1, 8
	s_mul_i32 s30, s1, 0xa000
	s_add_i32 s31, s31, 0x18000
	v_add_u32_e32 v6, s30, v151
	v_mov_b32_e32 v8, s31
	v_lshl_add_u32 v7, s1, 13, v0
	v_lshl_add_u32 v9, s1, 11, v39
	v_add_u32_e32 v22, 0x400, v9
	ds_read_b128 v[58:61], v6
	ds_read_b128 v[62:65], v6 offset:16
	ds_read_b128 v[66:69], v6 offset:32
	ds_read_b128 v[70:73], v6 offset:48
	ds_read_b128 v[74:77], v6 offset:64
	ds_read2st64_b32 v[118:119], v7 offset1:1
	ds_read_b128 v[120:123], v8
	ds_read_b128 v[78:81], v6 offset:1280
	ds_read_b128 v[82:85], v6 offset:1296
	ds_read_b128 v[86:89], v6 offset:1312
	ds_read_b128 v[90:93], v6 offset:1328
	ds_read_b128 v[94:97], v6 offset:1344
	ds_read_b128 v[98:101], v6 offset:2560
	ds_read_b128 v[102:105], v6 offset:2576
	ds_read_b128 v[106:109], v6 offset:2592
	ds_read_b128 v[110:113], v6 offset:2608
	ds_read_b128 v[114:117], v6 offset:2624
	ds_read2st64_b32 v[206:207], v7 offset0:2 offset1:3
	ds_read_b128 v[208:211], v8 offset:16
	s_waitcnt lgkmcnt(12)
	v_pk_mul_f32 v[10:11], v[2:3], v[58:59] op_sel_hi:[0,1]
	v_pk_fma_f32 v[10:11], v[2:3], v[60:61], v[10:11] op_sel:[1,0,0] op_sel_hi:[1,1,1]
	v_pk_fma_f32 v[10:11], v[4:5], v[62:63], v[10:11] op_sel_hi:[0,1,1]
	v_pk_fma_f32 v[10:11], v[4:5], v[64:65], v[10:11] op_sel:[1,0,0] op_sel_hi:[1,1,1]
	v_pk_mul_f32 v[18:19], v[74:75], v[118:119] op_sel_hi:[1,0]
	v_pk_mul_f32 v[20:21], v[76:77], v[118:119] op_sel_hi:[1,0]
	v_add_f32_dpp v10, v10, v10 quad_perm:[1,0,3,2] row_mask:0xf bank_mask:0xf bound_ctrl:1
	v_add_f32_dpp v11, v11, v11 quad_perm:[1,0,3,2] row_mask:0xf bank_mask:0xf bound_ctrl:1
	v_pk_fma_f32 v[18:19], v[2:3], v[66:67], v[18:19]
	v_add_f32_dpp v10, v10, v10 quad_perm:[2,3,0,1] row_mask:0xf bank_mask:0xf bound_ctrl:1
	v_add_f32_dpp v11, v11, v11 quad_perm:[2,3,0,1] row_mask:0xf bank_mask:0xf bound_ctrl:1
	v_pk_fma_f32 v[20:21], v[4:5], v[68:69], v[20:21]
	v_add_f32_dpp v10, v10, v10 row_half_mirror row_mask:0xf bank_mask:0xf bound_ctrl:1
	v_add_f32_dpp v11, v11, v11 row_half_mirror row_mask:0xf bank_mask:0xf bound_ctrl:1
	s_nop 0
	v_add_f32_dpp v10, v10, v10 row_mirror row_mask:0xf bank_mask:0xf bound_ctrl:1
	v_add_f32_dpp v11, v11, v11 row_mirror row_mask:0xf bank_mask:0xf bound_ctrl:1
	v_pk_fma_f32 v[2:3], v[70:71], v[10:11], v[18:19] op_sel_hi:[1,0,1]
	v_pk_fma_f32 v[4:5], v[72:73], v[10:11], v[20:21] op_sel_hi:[1,0,1]
	v_fmac_f32_e32 v11, v120, v10
	v_fmac_f32_e32 v11, v118, v121
	ds_read_b128 v[186:189], v6 offset:3840
	ds_read_b128 v[190:193], v6 offset:3856
	ds_read_b128 v[194:197], v6 offset:3872
	ds_read_b128 v[198:201], v6 offset:3888
	ds_read_b128 v[202:205], v6 offset:3904
	s_waitcnt lgkmcnt(12)
	v_pk_mul_f32 v[12:13], v[2:3], v[78:79] op_sel_hi:[0,1]
	v_pk_fma_f32 v[12:13], v[2:3], v[80:81], v[12:13] op_sel:[1,0,0] op_sel_hi:[1,1,1]
	v_pk_fma_f32 v[12:13], v[4:5], v[82:83], v[12:13] op_sel_hi:[0,1,1]
	v_pk_fma_f32 v[12:13], v[4:5], v[84:85], v[12:13] op_sel:[1,0,0] op_sel_hi:[1,1,1]
	v_pk_mul_f32 v[18:19], v[94:95], v[118:119] op_sel:[0,1] op_sel_hi:[1,1]
	v_pk_mul_f32 v[20:21], v[96:97], v[118:119] op_sel:[0,1] op_sel_hi:[1,1]
	v_add_f32_dpp v12, v12, v12 quad_perm:[1,0,3,2] row_mask:0xf bank_mask:0xf bound_ctrl:1
	v_add_f32_dpp v13, v13, v13 quad_perm:[1,0,3,2] row_mask:0xf bank_mask:0xf bound_ctrl:1
	v_pk_fma_f32 v[18:19], v[2:3], v[86:87], v[18:19]
	v_add_f32_dpp v12, v12, v12 quad_perm:[2,3,0,1] row_mask:0xf bank_mask:0xf bound_ctrl:1
	v_add_f32_dpp v13, v13, v13 quad_perm:[2,3,0,1] row_mask:0xf bank_mask:0xf bound_ctrl:1
	v_pk_fma_f32 v[20:21], v[4:5], v[88:89], v[20:21]
	v_add_f32_dpp v12, v12, v12 row_half_mirror row_mask:0xf bank_mask:0xf bound_ctrl:1
	v_add_f32_dpp v13, v13, v13 row_half_mirror row_mask:0xf bank_mask:0xf bound_ctrl:1
	s_nop 0
	v_add_f32_dpp v12, v12, v12 row_mirror row_mask:0xf bank_mask:0xf bound_ctrl:1
	v_add_f32_dpp v13, v13, v13 row_mirror row_mask:0xf bank_mask:0xf bound_ctrl:1
	v_pk_fma_f32 v[2:3], v[90:91], v[12:13], v[18:19] op_sel_hi:[1,0,1]
	v_pk_fma_f32 v[4:5], v[92:93], v[12:13], v[20:21] op_sel_hi:[1,0,1]
	v_fmac_f32_e32 v13, v122, v12
	v_fmac_f32_e32 v13, v119, v123
	ds_write2_b32 v9, v11, v13 offset1:16
	ds_read_b128 v[58:61], v6 offset:5120
	ds_read_b128 v[62:65], v6 offset:5136
	ds_read_b128 v[66:69], v6 offset:5152
	ds_read_b128 v[70:73], v6 offset:5168
	ds_read_b128 v[74:77], v6 offset:5184
	ds_read2st64_b32 v[118:119], v7 offset0:4 offset1:5
	ds_read_b128 v[120:123], v8 offset:32
	s_waitcnt lgkmcnt(13)
	v_pk_mul_f32 v[14:15], v[2:3], v[98:99] op_sel_hi:[0,1]
	v_pk_fma_f32 v[14:15], v[2:3], v[100:101], v[14:15] op_sel:[1,0,0] op_sel_hi:[1,1,1]
	v_pk_fma_f32 v[14:15], v[4:5], v[102:103], v[14:15] op_sel_hi:[0,1,1]
	v_pk_fma_f32 v[14:15], v[4:5], v[104:105], v[14:15] op_sel:[1,0,0] op_sel_hi:[1,1,1]
	v_pk_mul_f32 v[18:19], v[114:115], v[206:207] op_sel_hi:[1,0]
	v_pk_mul_f32 v[20:21], v[116:117], v[206:207] op_sel_hi:[1,0]
	v_add_f32_dpp v14, v14, v14 quad_perm:[1,0,3,2] row_mask:0xf bank_mask:0xf bound_ctrl:1
	v_add_f32_dpp v15, v15, v15 quad_perm:[1,0,3,2] row_mask:0xf bank_mask:0xf bound_ctrl:1
	v_pk_fma_f32 v[18:19], v[2:3], v[106:107], v[18:19]
	v_add_f32_dpp v14, v14, v14 quad_perm:[2,3,0,1] row_mask:0xf bank_mask:0xf bound_ctrl:1
	v_add_f32_dpp v15, v15, v15 quad_perm:[2,3,0,1] row_mask:0xf bank_mask:0xf bound_ctrl:1
	v_pk_fma_f32 v[20:21], v[4:5], v[108:109], v[20:21]
	v_add_f32_dpp v14, v14, v14 row_half_mirror row_mask:0xf bank_mask:0xf bound_ctrl:1
	v_add_f32_dpp v15, v15, v15 row_half_mirror row_mask:0xf bank_mask:0xf bound_ctrl:1
	s_nop 0
	v_add_f32_dpp v14, v14, v14 row_mirror row_mask:0xf bank_mask:0xf bound_ctrl:1
	v_add_f32_dpp v15, v15, v15 row_mirror row_mask:0xf bank_mask:0xf bound_ctrl:1
	v_pk_fma_f32 v[2:3], v[110:111], v[14:15], v[18:19] op_sel_hi:[1,0,1]
	v_pk_fma_f32 v[4:5], v[112:113], v[14:15], v[20:21] op_sel_hi:[1,0,1]
	v_fmac_f32_e32 v15, v208, v14
	v_fmac_f32_e32 v15, v206, v209
	ds_read_b128 v[78:81], v6 offset:6400
	ds_read_b128 v[82:85], v6 offset:6416
	ds_read_b128 v[86:89], v6 offset:6432
	ds_read_b128 v[90:93], v6 offset:6448
	ds_read_b128 v[94:97], v6 offset:6464
	s_waitcnt lgkmcnt(13)
	v_pk_mul_f32 v[16:17], v[2:3], v[186:187] op_sel_hi:[0,1]
	v_pk_fma_f32 v[16:17], v[2:3], v[188:189], v[16:17] op_sel:[1,0,0] op_sel_hi:[1,1,1]
	v_pk_fma_f32 v[16:17], v[4:5], v[190:191], v[16:17] op_sel_hi:[0,1,1]
	v_pk_fma_f32 v[16:17], v[4:5], v[192:193], v[16:17] op_sel:[1,0,0] op_sel_hi:[1,1,1]
	v_pk_mul_f32 v[18:19], v[202:203], v[206:207] op_sel:[0,1] op_sel_hi:[1,1]
	v_pk_mul_f32 v[20:21], v[204:205], v[206:207] op_sel:[0,1] op_sel_hi:[1,1]
	v_add_f32_dpp v16, v16, v16 quad_perm:[1,0,3,2] row_mask:0xf bank_mask:0xf bound_ctrl:1
	v_add_f32_dpp v17, v17, v17 quad_perm:[1,0,3,2] row_mask:0xf bank_mask:0xf bound_ctrl:1
	v_pk_fma_f32 v[18:19], v[2:3], v[194:195], v[18:19]
	v_add_f32_dpp v16, v16, v16 quad_perm:[2,3,0,1] row_mask:0xf bank_mask:0xf bound_ctrl:1
	v_add_f32_dpp v17, v17, v17 quad_perm:[2,3,0,1] row_mask:0xf bank_mask:0xf bound_ctrl:1
	v_pk_fma_f32 v[20:21], v[4:5], v[196:197], v[20:21]
	v_add_f32_dpp v16, v16, v16 row_half_mirror row_mask:0xf bank_mask:0xf bound_ctrl:1
	v_add_f32_dpp v17, v17, v17 row_half_mirror row_mask:0xf bank_mask:0xf bound_ctrl:1
	s_nop 0
	v_add_f32_dpp v16, v16, v16 row_mirror row_mask:0xf bank_mask:0xf bound_ctrl:1
	v_add_f32_dpp v17, v17, v17 row_mirror row_mask:0xf bank_mask:0xf bound_ctrl:1
	v_pk_fma_f32 v[2:3], v[198:199], v[16:17], v[18:19] op_sel_hi:[1,0,1]
	v_pk_fma_f32 v[4:5], v[200:201], v[16:17], v[20:21] op_sel_hi:[1,0,1]
	v_fmac_f32_e32 v17, v210, v16
	v_fmac_f32_e32 v17, v207, v211
	ds_write2_b32 v9, v15, v17 offset0:32 offset1:48
	ds_read_b128 v[98:101], v6 offset:7680
	ds_read_b128 v[102:105], v6 offset:7696
	ds_read_b128 v[106:109], v6 offset:7712
	ds_read_b128 v[110:113], v6 offset:7728
	ds_read_b128 v[114:117], v6 offset:7744
	ds_read2st64_b32 v[206:207], v7 offset0:6 offset1:7
	ds_read_b128 v[208:211], v8 offset:48
	s_waitcnt lgkmcnt(13)
	v_pk_mul_f32 v[10:11], v[2:3], v[58:59] op_sel_hi:[0,1]
	v_pk_fma_f32 v[10:11], v[2:3], v[60:61], v[10:11] op_sel:[1,0,0] op_sel_hi:[1,1,1]
	v_pk_fma_f32 v[10:11], v[4:5], v[62:63], v[10:11] op_sel_hi:[0,1,1]
	v_pk_fma_f32 v[10:11], v[4:5], v[64:65], v[10:11] op_sel:[1,0,0] op_sel_hi:[1,1,1]
	v_pk_mul_f32 v[18:19], v[74:75], v[118:119] op_sel_hi:[1,0]
	v_pk_mul_f32 v[20:21], v[76:77], v[118:119] op_sel_hi:[1,0]
	v_add_f32_dpp v10, v10, v10 quad_perm:[1,0,3,2] row_mask:0xf bank_mask:0xf bound_ctrl:1
	v_add_f32_dpp v11, v11, v11 quad_perm:[1,0,3,2] row_mask:0xf bank_mask:0xf bound_ctrl:1
	v_pk_fma_f32 v[18:19], v[2:3], v[66:67], v[18:19]
	v_add_f32_dpp v10, v10, v10 quad_perm:[2,3,0,1] row_mask:0xf bank_mask:0xf bound_ctrl:1
	v_add_f32_dpp v11, v11, v11 quad_perm:[2,3,0,1] row_mask:0xf bank_mask:0xf bound_ctrl:1
	v_pk_fma_f32 v[20:21], v[4:5], v[68:69], v[20:21]
	v_add_f32_dpp v10, v10, v10 row_half_mirror row_mask:0xf bank_mask:0xf bound_ctrl:1
	v_add_f32_dpp v11, v11, v11 row_half_mirror row_mask:0xf bank_mask:0xf bound_ctrl:1
	s_nop 0
	v_add_f32_dpp v10, v10, v10 row_mirror row_mask:0xf bank_mask:0xf bound_ctrl:1
	v_add_f32_dpp v11, v11, v11 row_mirror row_mask:0xf bank_mask:0xf bound_ctrl:1
	v_pk_fma_f32 v[2:3], v[70:71], v[10:11], v[18:19] op_sel_hi:[1,0,1]
	v_pk_fma_f32 v[4:5], v[72:73], v[10:11], v[20:21] op_sel_hi:[1,0,1]
	v_fmac_f32_e32 v11, v120, v10
	v_fmac_f32_e32 v11, v118, v121
	ds_read_b128 v[186:189], v6 offset:8960
	ds_read_b128 v[190:193], v6 offset:8976
	ds_read_b128 v[194:197], v6 offset:8992
	ds_read_b128 v[198:201], v6 offset:9008
	ds_read_b128 v[202:205], v6 offset:9024
	s_waitcnt lgkmcnt(13)
	v_pk_mul_f32 v[12:13], v[2:3], v[78:79] op_sel_hi:[0,1]
	v_pk_fma_f32 v[12:13], v[2:3], v[80:81], v[12:13] op_sel:[1,0,0] op_sel_hi:[1,1,1]
	v_pk_fma_f32 v[12:13], v[4:5], v[82:83], v[12:13] op_sel_hi:[0,1,1]
	v_pk_fma_f32 v[12:13], v[4:5], v[84:85], v[12:13] op_sel:[1,0,0] op_sel_hi:[1,1,1]
	v_pk_mul_f32 v[18:19], v[94:95], v[118:119] op_sel:[0,1] op_sel_hi:[1,1]
	v_pk_mul_f32 v[20:21], v[96:97], v[118:119] op_sel:[0,1] op_sel_hi:[1,1]
	v_add_f32_dpp v12, v12, v12 quad_perm:[1,0,3,2] row_mask:0xf bank_mask:0xf bound_ctrl:1
	v_add_f32_dpp v13, v13, v13 quad_perm:[1,0,3,2] row_mask:0xf bank_mask:0xf bound_ctrl:1
	v_pk_fma_f32 v[18:19], v[2:3], v[86:87], v[18:19]
	v_add_f32_dpp v12, v12, v12 quad_perm:[2,3,0,1] row_mask:0xf bank_mask:0xf bound_ctrl:1
	v_add_f32_dpp v13, v13, v13 quad_perm:[2,3,0,1] row_mask:0xf bank_mask:0xf bound_ctrl:1
	v_pk_fma_f32 v[20:21], v[4:5], v[88:89], v[20:21]
	v_add_f32_dpp v12, v12, v12 row_half_mirror row_mask:0xf bank_mask:0xf bound_ctrl:1
	v_add_f32_dpp v13, v13, v13 row_half_mirror row_mask:0xf bank_mask:0xf bound_ctrl:1
	s_nop 0
	v_add_f32_dpp v12, v12, v12 row_mirror row_mask:0xf bank_mask:0xf bound_ctrl:1
	v_add_f32_dpp v13, v13, v13 row_mirror row_mask:0xf bank_mask:0xf bound_ctrl:1
	v_pk_fma_f32 v[2:3], v[90:91], v[12:13], v[18:19] op_sel_hi:[1,0,1]
	v_pk_fma_f32 v[4:5], v[92:93], v[12:13], v[20:21] op_sel_hi:[1,0,1]
	v_fmac_f32_e32 v13, v122, v12
	v_fmac_f32_e32 v13, v119, v123
	ds_write2_b32 v9, v11, v13 offset0:64 offset1:80
	ds_read_b128 v[58:61], v6 offset:10240
	ds_read_b128 v[62:65], v6 offset:10256
	ds_read_b128 v[66:69], v6 offset:10272
	ds_read_b128 v[70:73], v6 offset:10288
	ds_read_b128 v[74:77], v6 offset:10304
	ds_read2st64_b32 v[118:119], v7 offset0:8 offset1:9
	ds_read_b128 v[120:123], v8 offset:64
	s_waitcnt lgkmcnt(13)
	v_pk_mul_f32 v[14:15], v[2:3], v[98:99] op_sel_hi:[0,1]
	v_pk_fma_f32 v[14:15], v[2:3], v[100:101], v[14:15] op_sel:[1,0,0] op_sel_hi:[1,1,1]
	v_pk_fma_f32 v[14:15], v[4:5], v[102:103], v[14:15] op_sel_hi:[0,1,1]
	v_pk_fma_f32 v[14:15], v[4:5], v[104:105], v[14:15] op_sel:[1,0,0] op_sel_hi:[1,1,1]
	v_pk_mul_f32 v[18:19], v[114:115], v[206:207] op_sel_hi:[1,0]
	v_pk_mul_f32 v[20:21], v[116:117], v[206:207] op_sel_hi:[1,0]
	v_add_f32_dpp v14, v14, v14 quad_perm:[1,0,3,2] row_mask:0xf bank_mask:0xf bound_ctrl:1
	v_add_f32_dpp v15, v15, v15 quad_perm:[1,0,3,2] row_mask:0xf bank_mask:0xf bound_ctrl:1
	v_pk_fma_f32 v[18:19], v[2:3], v[106:107], v[18:19]
	v_add_f32_dpp v14, v14, v14 quad_perm:[2,3,0,1] row_mask:0xf bank_mask:0xf bound_ctrl:1
	v_add_f32_dpp v15, v15, v15 quad_perm:[2,3,0,1] row_mask:0xf bank_mask:0xf bound_ctrl:1
	v_pk_fma_f32 v[20:21], v[4:5], v[108:109], v[20:21]
	v_add_f32_dpp v14, v14, v14 row_half_mirror row_mask:0xf bank_mask:0xf bound_ctrl:1
	v_add_f32_dpp v15, v15, v15 row_half_mirror row_mask:0xf bank_mask:0xf bound_ctrl:1
	s_nop 0
	v_add_f32_dpp v14, v14, v14 row_mirror row_mask:0xf bank_mask:0xf bound_ctrl:1
	v_add_f32_dpp v15, v15, v15 row_mirror row_mask:0xf bank_mask:0xf bound_ctrl:1
	v_pk_fma_f32 v[2:3], v[110:111], v[14:15], v[18:19] op_sel_hi:[1,0,1]
	v_pk_fma_f32 v[4:5], v[112:113], v[14:15], v[20:21] op_sel_hi:[1,0,1]
	v_fmac_f32_e32 v15, v208, v14
	v_fmac_f32_e32 v15, v206, v209
	ds_read_b128 v[78:81], v6 offset:11520
	ds_read_b128 v[82:85], v6 offset:11536
	ds_read_b128 v[86:89], v6 offset:11552
	ds_read_b128 v[90:93], v6 offset:11568
	ds_read_b128 v[94:97], v6 offset:11584
	s_waitcnt lgkmcnt(13)
	v_pk_mul_f32 v[16:17], v[2:3], v[186:187] op_sel_hi:[0,1]
	v_pk_fma_f32 v[16:17], v[2:3], v[188:189], v[16:17] op_sel:[1,0,0] op_sel_hi:[1,1,1]
	v_pk_fma_f32 v[16:17], v[4:5], v[190:191], v[16:17] op_sel_hi:[0,1,1]
	v_pk_fma_f32 v[16:17], v[4:5], v[192:193], v[16:17] op_sel:[1,0,0] op_sel_hi:[1,1,1]
	v_pk_mul_f32 v[18:19], v[202:203], v[206:207] op_sel:[0,1] op_sel_hi:[1,1]
	v_pk_mul_f32 v[20:21], v[204:205], v[206:207] op_sel:[0,1] op_sel_hi:[1,1]
	v_add_f32_dpp v16, v16, v16 quad_perm:[1,0,3,2] row_mask:0xf bank_mask:0xf bound_ctrl:1
	v_add_f32_dpp v17, v17, v17 quad_perm:[1,0,3,2] row_mask:0xf bank_mask:0xf bound_ctrl:1
	v_pk_fma_f32 v[18:19], v[2:3], v[194:195], v[18:19]
	v_add_f32_dpp v16, v16, v16 quad_perm:[2,3,0,1] row_mask:0xf bank_mask:0xf bound_ctrl:1
	v_add_f32_dpp v17, v17, v17 quad_perm:[2,3,0,1] row_mask:0xf bank_mask:0xf bound_ctrl:1
	v_pk_fma_f32 v[20:21], v[4:5], v[196:197], v[20:21]
	v_add_f32_dpp v16, v16, v16 row_half_mirror row_mask:0xf bank_mask:0xf bound_ctrl:1
	v_add_f32_dpp v17, v17, v17 row_half_mirror row_mask:0xf bank_mask:0xf bound_ctrl:1
	s_nop 0
	v_add_f32_dpp v16, v16, v16 row_mirror row_mask:0xf bank_mask:0xf bound_ctrl:1
	v_add_f32_dpp v17, v17, v17 row_mirror row_mask:0xf bank_mask:0xf bound_ctrl:1
	v_pk_fma_f32 v[2:3], v[198:199], v[16:17], v[18:19] op_sel_hi:[1,0,1]
	v_pk_fma_f32 v[4:5], v[200:201], v[16:17], v[20:21] op_sel_hi:[1,0,1]
	v_fmac_f32_e32 v17, v210, v16
	v_fmac_f32_e32 v17, v207, v211
	ds_write2_b32 v9, v15, v17 offset0:96 offset1:112
	ds_read_b128 v[98:101], v6 offset:12800
	ds_read_b128 v[102:105], v6 offset:12816
	ds_read_b128 v[106:109], v6 offset:12832
	ds_read_b128 v[110:113], v6 offset:12848
	ds_read_b128 v[114:117], v6 offset:12864
	ds_read2st64_b32 v[206:207], v7 offset0:10 offset1:11
	ds_read_b128 v[208:211], v8 offset:80
	s_waitcnt lgkmcnt(13)
	v_pk_mul_f32 v[10:11], v[2:3], v[58:59] op_sel_hi:[0,1]
	v_pk_fma_f32 v[10:11], v[2:3], v[60:61], v[10:11] op_sel:[1,0,0] op_sel_hi:[1,1,1]
	v_pk_fma_f32 v[10:11], v[4:5], v[62:63], v[10:11] op_sel_hi:[0,1,1]
	v_pk_fma_f32 v[10:11], v[4:5], v[64:65], v[10:11] op_sel:[1,0,0] op_sel_hi:[1,1,1]
	v_pk_mul_f32 v[18:19], v[74:75], v[118:119] op_sel_hi:[1,0]
	v_pk_mul_f32 v[20:21], v[76:77], v[118:119] op_sel_hi:[1,0]
	v_add_f32_dpp v10, v10, v10 quad_perm:[1,0,3,2] row_mask:0xf bank_mask:0xf bound_ctrl:1
	v_add_f32_dpp v11, v11, v11 quad_perm:[1,0,3,2] row_mask:0xf bank_mask:0xf bound_ctrl:1
	v_pk_fma_f32 v[18:19], v[2:3], v[66:67], v[18:19]
	v_add_f32_dpp v10, v10, v10 quad_perm:[2,3,0,1] row_mask:0xf bank_mask:0xf bound_ctrl:1
	v_add_f32_dpp v11, v11, v11 quad_perm:[2,3,0,1] row_mask:0xf bank_mask:0xf bound_ctrl:1
	v_pk_fma_f32 v[20:21], v[4:5], v[68:69], v[20:21]
	v_add_f32_dpp v10, v10, v10 row_half_mirror row_mask:0xf bank_mask:0xf bound_ctrl:1
	v_add_f32_dpp v11, v11, v11 row_half_mirror row_mask:0xf bank_mask:0xf bound_ctrl:1
	s_nop 0
	v_add_f32_dpp v10, v10, v10 row_mirror row_mask:0xf bank_mask:0xf bound_ctrl:1
	v_add_f32_dpp v11, v11, v11 row_mirror row_mask:0xf bank_mask:0xf bound_ctrl:1
	v_pk_fma_f32 v[2:3], v[70:71], v[10:11], v[18:19] op_sel_hi:[1,0,1]
	v_pk_fma_f32 v[4:5], v[72:73], v[10:11], v[20:21] op_sel_hi:[1,0,1]
	v_fmac_f32_e32 v11, v120, v10
	v_fmac_f32_e32 v11, v118, v121
	ds_read_b128 v[186:189], v6 offset:14080
	ds_read_b128 v[190:193], v6 offset:14096
	ds_read_b128 v[194:197], v6 offset:14112
	ds_read_b128 v[198:201], v6 offset:14128
	ds_read_b128 v[202:205], v6 offset:14144
	s_waitcnt lgkmcnt(13)
	v_pk_mul_f32 v[12:13], v[2:3], v[78:79] op_sel_hi:[0,1]
	v_pk_fma_f32 v[12:13], v[2:3], v[80:81], v[12:13] op_sel:[1,0,0] op_sel_hi:[1,1,1]
	v_pk_fma_f32 v[12:13], v[4:5], v[82:83], v[12:13] op_sel_hi:[0,1,1]
	v_pk_fma_f32 v[12:13], v[4:5], v[84:85], v[12:13] op_sel:[1,0,0] op_sel_hi:[1,1,1]
	v_pk_mul_f32 v[18:19], v[94:95], v[118:119] op_sel:[0,1] op_sel_hi:[1,1]
	v_pk_mul_f32 v[20:21], v[96:97], v[118:119] op_sel:[0,1] op_sel_hi:[1,1]
	v_add_f32_dpp v12, v12, v12 quad_perm:[1,0,3,2] row_mask:0xf bank_mask:0xf bound_ctrl:1
	v_add_f32_dpp v13, v13, v13 quad_perm:[1,0,3,2] row_mask:0xf bank_mask:0xf bound_ctrl:1
	v_pk_fma_f32 v[18:19], v[2:3], v[86:87], v[18:19]
	v_add_f32_dpp v12, v12, v12 quad_perm:[2,3,0,1] row_mask:0xf bank_mask:0xf bound_ctrl:1
	v_add_f32_dpp v13, v13, v13 quad_perm:[2,3,0,1] row_mask:0xf bank_mask:0xf bound_ctrl:1
	v_pk_fma_f32 v[20:21], v[4:5], v[88:89], v[20:21]
	v_add_f32_dpp v12, v12, v12 row_half_mirror row_mask:0xf bank_mask:0xf bound_ctrl:1
	v_add_f32_dpp v13, v13, v13 row_half_mirror row_mask:0xf bank_mask:0xf bound_ctrl:1
	s_nop 0
	v_add_f32_dpp v12, v12, v12 row_mirror row_mask:0xf bank_mask:0xf bound_ctrl:1
	v_add_f32_dpp v13, v13, v13 row_mirror row_mask:0xf bank_mask:0xf bound_ctrl:1
	v_pk_fma_f32 v[2:3], v[90:91], v[12:13], v[18:19] op_sel_hi:[1,0,1]
	v_pk_fma_f32 v[4:5], v[92:93], v[12:13], v[20:21] op_sel_hi:[1,0,1]
	v_fmac_f32_e32 v13, v122, v12
	v_fmac_f32_e32 v13, v119, v123
	ds_write2_b32 v9, v11, v13 offset0:128 offset1:144
	ds_read_b128 v[58:61], v6 offset:15360
	ds_read_b128 v[62:65], v6 offset:15376
	ds_read_b128 v[66:69], v6 offset:15392
	ds_read_b128 v[70:73], v6 offset:15408
	ds_read_b128 v[74:77], v6 offset:15424
	ds_read2st64_b32 v[118:119], v7 offset0:12 offset1:13
	ds_read_b128 v[120:123], v8 offset:96
	s_waitcnt lgkmcnt(13)
	v_pk_mul_f32 v[14:15], v[2:3], v[98:99] op_sel_hi:[0,1]
	v_pk_fma_f32 v[14:15], v[2:3], v[100:101], v[14:15] op_sel:[1,0,0] op_sel_hi:[1,1,1]
	v_pk_fma_f32 v[14:15], v[4:5], v[102:103], v[14:15] op_sel_hi:[0,1,1]
	v_pk_fma_f32 v[14:15], v[4:5], v[104:105], v[14:15] op_sel:[1,0,0] op_sel_hi:[1,1,1]
	v_pk_mul_f32 v[18:19], v[114:115], v[206:207] op_sel_hi:[1,0]
	v_pk_mul_f32 v[20:21], v[116:117], v[206:207] op_sel_hi:[1,0]
	v_add_f32_dpp v14, v14, v14 quad_perm:[1,0,3,2] row_mask:0xf bank_mask:0xf bound_ctrl:1
	v_add_f32_dpp v15, v15, v15 quad_perm:[1,0,3,2] row_mask:0xf bank_mask:0xf bound_ctrl:1
	v_pk_fma_f32 v[18:19], v[2:3], v[106:107], v[18:19]
	v_add_f32_dpp v14, v14, v14 quad_perm:[2,3,0,1] row_mask:0xf bank_mask:0xf bound_ctrl:1
	v_add_f32_dpp v15, v15, v15 quad_perm:[2,3,0,1] row_mask:0xf bank_mask:0xf bound_ctrl:1
	v_pk_fma_f32 v[20:21], v[4:5], v[108:109], v[20:21]
	v_add_f32_dpp v14, v14, v14 row_half_mirror row_mask:0xf bank_mask:0xf bound_ctrl:1
	v_add_f32_dpp v15, v15, v15 row_half_mirror row_mask:0xf bank_mask:0xf bound_ctrl:1
	s_nop 0
	v_add_f32_dpp v14, v14, v14 row_mirror row_mask:0xf bank_mask:0xf bound_ctrl:1
	v_add_f32_dpp v15, v15, v15 row_mirror row_mask:0xf bank_mask:0xf bound_ctrl:1
	v_pk_fma_f32 v[2:3], v[110:111], v[14:15], v[18:19] op_sel_hi:[1,0,1]
	v_pk_fma_f32 v[4:5], v[112:113], v[14:15], v[20:21] op_sel_hi:[1,0,1]
	v_fmac_f32_e32 v15, v208, v14
	v_fmac_f32_e32 v15, v206, v209
	ds_read_b128 v[78:81], v6 offset:16640
	ds_read_b128 v[82:85], v6 offset:16656
	ds_read_b128 v[86:89], v6 offset:16672
	ds_read_b128 v[90:93], v6 offset:16688
	ds_read_b128 v[94:97], v6 offset:16704
	s_waitcnt lgkmcnt(13)
	v_pk_mul_f32 v[16:17], v[2:3], v[186:187] op_sel_hi:[0,1]
	v_pk_fma_f32 v[16:17], v[2:3], v[188:189], v[16:17] op_sel:[1,0,0] op_sel_hi:[1,1,1]
	v_pk_fma_f32 v[16:17], v[4:5], v[190:191], v[16:17] op_sel_hi:[0,1,1]
	v_pk_fma_f32 v[16:17], v[4:5], v[192:193], v[16:17] op_sel:[1,0,0] op_sel_hi:[1,1,1]
	v_pk_mul_f32 v[18:19], v[202:203], v[206:207] op_sel:[0,1] op_sel_hi:[1,1]
	v_pk_mul_f32 v[20:21], v[204:205], v[206:207] op_sel:[0,1] op_sel_hi:[1,1]
	v_add_f32_dpp v16, v16, v16 quad_perm:[1,0,3,2] row_mask:0xf bank_mask:0xf bound_ctrl:1
	v_add_f32_dpp v17, v17, v17 quad_perm:[1,0,3,2] row_mask:0xf bank_mask:0xf bound_ctrl:1
	v_pk_fma_f32 v[18:19], v[2:3], v[194:195], v[18:19]
	v_add_f32_dpp v16, v16, v16 quad_perm:[2,3,0,1] row_mask:0xf bank_mask:0xf bound_ctrl:1
	v_add_f32_dpp v17, v17, v17 quad_perm:[2,3,0,1] row_mask:0xf bank_mask:0xf bound_ctrl:1
	v_pk_fma_f32 v[20:21], v[4:5], v[196:197], v[20:21]
	v_add_f32_dpp v16, v16, v16 row_half_mirror row_mask:0xf bank_mask:0xf bound_ctrl:1
	v_add_f32_dpp v17, v17, v17 row_half_mirror row_mask:0xf bank_mask:0xf bound_ctrl:1
	s_nop 0
	v_add_f32_dpp v16, v16, v16 row_mirror row_mask:0xf bank_mask:0xf bound_ctrl:1
	v_add_f32_dpp v17, v17, v17 row_mirror row_mask:0xf bank_mask:0xf bound_ctrl:1
	v_pk_fma_f32 v[2:3], v[198:199], v[16:17], v[18:19] op_sel_hi:[1,0,1]
	v_pk_fma_f32 v[4:5], v[200:201], v[16:17], v[20:21] op_sel_hi:[1,0,1]
	v_fmac_f32_e32 v17, v210, v16
	v_fmac_f32_e32 v17, v207, v211
	ds_write2_b32 v9, v15, v17 offset0:160 offset1:176
	ds_read_b128 v[98:101], v6 offset:17920
	ds_read_b128 v[102:105], v6 offset:17936
	ds_read_b128 v[106:109], v6 offset:17952
	ds_read_b128 v[110:113], v6 offset:17968
	ds_read_b128 v[114:117], v6 offset:17984
	ds_read2st64_b32 v[206:207], v7 offset0:14 offset1:15
	ds_read_b128 v[208:211], v8 offset:112
	s_waitcnt lgkmcnt(13)
	v_pk_mul_f32 v[10:11], v[2:3], v[58:59] op_sel_hi:[0,1]
	v_pk_fma_f32 v[10:11], v[2:3], v[60:61], v[10:11] op_sel:[1,0,0] op_sel_hi:[1,1,1]
	v_pk_fma_f32 v[10:11], v[4:5], v[62:63], v[10:11] op_sel_hi:[0,1,1]
	v_pk_fma_f32 v[10:11], v[4:5], v[64:65], v[10:11] op_sel:[1,0,0] op_sel_hi:[1,1,1]
	v_pk_mul_f32 v[18:19], v[74:75], v[118:119] op_sel_hi:[1,0]
	v_pk_mul_f32 v[20:21], v[76:77], v[118:119] op_sel_hi:[1,0]
	v_add_f32_dpp v10, v10, v10 quad_perm:[1,0,3,2] row_mask:0xf bank_mask:0xf bound_ctrl:1
	v_add_f32_dpp v11, v11, v11 quad_perm:[1,0,3,2] row_mask:0xf bank_mask:0xf bound_ctrl:1
	v_pk_fma_f32 v[18:19], v[2:3], v[66:67], v[18:19]
	v_add_f32_dpp v10, v10, v10 quad_perm:[2,3,0,1] row_mask:0xf bank_mask:0xf bound_ctrl:1
	v_add_f32_dpp v11, v11, v11 quad_perm:[2,3,0,1] row_mask:0xf bank_mask:0xf bound_ctrl:1
	v_pk_fma_f32 v[20:21], v[4:5], v[68:69], v[20:21]
	v_add_f32_dpp v10, v10, v10 row_half_mirror row_mask:0xf bank_mask:0xf bound_ctrl:1
	v_add_f32_dpp v11, v11, v11 row_half_mirror row_mask:0xf bank_mask:0xf bound_ctrl:1
	s_nop 0
	v_add_f32_dpp v10, v10, v10 row_mirror row_mask:0xf bank_mask:0xf bound_ctrl:1
	v_add_f32_dpp v11, v11, v11 row_mirror row_mask:0xf bank_mask:0xf bound_ctrl:1
	v_pk_fma_f32 v[2:3], v[70:71], v[10:11], v[18:19] op_sel_hi:[1,0,1]
	v_pk_fma_f32 v[4:5], v[72:73], v[10:11], v[20:21] op_sel_hi:[1,0,1]
	v_fmac_f32_e32 v11, v120, v10
	v_fmac_f32_e32 v11, v118, v121
	ds_read_b128 v[186:189], v6 offset:19200
	ds_read_b128 v[190:193], v6 offset:19216
	ds_read_b128 v[194:197], v6 offset:19232
	ds_read_b128 v[198:201], v6 offset:19248
	ds_read_b128 v[202:205], v6 offset:19264
	s_waitcnt lgkmcnt(13)
	v_pk_mul_f32 v[12:13], v[2:3], v[78:79] op_sel_hi:[0,1]
	v_pk_fma_f32 v[12:13], v[2:3], v[80:81], v[12:13] op_sel:[1,0,0] op_sel_hi:[1,1,1]
	v_pk_fma_f32 v[12:13], v[4:5], v[82:83], v[12:13] op_sel_hi:[0,1,1]
	v_pk_fma_f32 v[12:13], v[4:5], v[84:85], v[12:13] op_sel:[1,0,0] op_sel_hi:[1,1,1]
	v_pk_mul_f32 v[18:19], v[94:95], v[118:119] op_sel:[0,1] op_sel_hi:[1,1]
	v_pk_mul_f32 v[20:21], v[96:97], v[118:119] op_sel:[0,1] op_sel_hi:[1,1]
	v_add_f32_dpp v12, v12, v12 quad_perm:[1,0,3,2] row_mask:0xf bank_mask:0xf bound_ctrl:1
	v_add_f32_dpp v13, v13, v13 quad_perm:[1,0,3,2] row_mask:0xf bank_mask:0xf bound_ctrl:1
	v_pk_fma_f32 v[18:19], v[2:3], v[86:87], v[18:19]
	v_add_f32_dpp v12, v12, v12 quad_perm:[2,3,0,1] row_mask:0xf bank_mask:0xf bound_ctrl:1
	v_add_f32_dpp v13, v13, v13 quad_perm:[2,3,0,1] row_mask:0xf bank_mask:0xf bound_ctrl:1
	v_pk_fma_f32 v[20:21], v[4:5], v[88:89], v[20:21]
	v_add_f32_dpp v12, v12, v12 row_half_mirror row_mask:0xf bank_mask:0xf bound_ctrl:1
	v_add_f32_dpp v13, v13, v13 row_half_mirror row_mask:0xf bank_mask:0xf bound_ctrl:1
	s_nop 0
	v_add_f32_dpp v12, v12, v12 row_mirror row_mask:0xf bank_mask:0xf bound_ctrl:1
	v_add_f32_dpp v13, v13, v13 row_mirror row_mask:0xf bank_mask:0xf bound_ctrl:1
	v_pk_fma_f32 v[2:3], v[90:91], v[12:13], v[18:19] op_sel_hi:[1,0,1]
	v_pk_fma_f32 v[4:5], v[92:93], v[12:13], v[20:21] op_sel_hi:[1,0,1]
	v_fmac_f32_e32 v13, v122, v12
	v_fmac_f32_e32 v13, v119, v123
	ds_write2_b32 v9, v11, v13 offset0:192 offset1:208
	ds_read_b128 v[58:61], v6 offset:20480
	ds_read_b128 v[62:65], v6 offset:20496
	ds_read_b128 v[66:69], v6 offset:20512
	ds_read_b128 v[70:73], v6 offset:20528
	ds_read_b128 v[74:77], v6 offset:20544
	ds_read2st64_b32 v[118:119], v7 offset0:16 offset1:17
	ds_read_b128 v[120:123], v8 offset:128
	s_waitcnt lgkmcnt(13)
	v_pk_mul_f32 v[14:15], v[2:3], v[98:99] op_sel_hi:[0,1]
	v_pk_fma_f32 v[14:15], v[2:3], v[100:101], v[14:15] op_sel:[1,0,0] op_sel_hi:[1,1,1]
	v_pk_fma_f32 v[14:15], v[4:5], v[102:103], v[14:15] op_sel_hi:[0,1,1]
	v_pk_fma_f32 v[14:15], v[4:5], v[104:105], v[14:15] op_sel:[1,0,0] op_sel_hi:[1,1,1]
	v_pk_mul_f32 v[18:19], v[114:115], v[206:207] op_sel_hi:[1,0]
	v_pk_mul_f32 v[20:21], v[116:117], v[206:207] op_sel_hi:[1,0]
	v_add_f32_dpp v14, v14, v14 quad_perm:[1,0,3,2] row_mask:0xf bank_mask:0xf bound_ctrl:1
	v_add_f32_dpp v15, v15, v15 quad_perm:[1,0,3,2] row_mask:0xf bank_mask:0xf bound_ctrl:1
	v_pk_fma_f32 v[18:19], v[2:3], v[106:107], v[18:19]
	v_add_f32_dpp v14, v14, v14 quad_perm:[2,3,0,1] row_mask:0xf bank_mask:0xf bound_ctrl:1
	v_add_f32_dpp v15, v15, v15 quad_perm:[2,3,0,1] row_mask:0xf bank_mask:0xf bound_ctrl:1
	v_pk_fma_f32 v[20:21], v[4:5], v[108:109], v[20:21]
	v_add_f32_dpp v14, v14, v14 row_half_mirror row_mask:0xf bank_mask:0xf bound_ctrl:1
	v_add_f32_dpp v15, v15, v15 row_half_mirror row_mask:0xf bank_mask:0xf bound_ctrl:1
	s_nop 0
	v_add_f32_dpp v14, v14, v14 row_mirror row_mask:0xf bank_mask:0xf bound_ctrl:1
	v_add_f32_dpp v15, v15, v15 row_mirror row_mask:0xf bank_mask:0xf bound_ctrl:1
	v_pk_fma_f32 v[2:3], v[110:111], v[14:15], v[18:19] op_sel_hi:[1,0,1]
	v_pk_fma_f32 v[4:5], v[112:113], v[14:15], v[20:21] op_sel_hi:[1,0,1]
	v_fmac_f32_e32 v15, v208, v14
	v_fmac_f32_e32 v15, v206, v209
	ds_read_b128 v[78:81], v6 offset:21760
	ds_read_b128 v[82:85], v6 offset:21776
	ds_read_b128 v[86:89], v6 offset:21792
	ds_read_b128 v[90:93], v6 offset:21808
	ds_read_b128 v[94:97], v6 offset:21824
	s_waitcnt lgkmcnt(13)
	v_pk_mul_f32 v[16:17], v[2:3], v[186:187] op_sel_hi:[0,1]
	v_pk_fma_f32 v[16:17], v[2:3], v[188:189], v[16:17] op_sel:[1,0,0] op_sel_hi:[1,1,1]
	v_pk_fma_f32 v[16:17], v[4:5], v[190:191], v[16:17] op_sel_hi:[0,1,1]
	v_pk_fma_f32 v[16:17], v[4:5], v[192:193], v[16:17] op_sel:[1,0,0] op_sel_hi:[1,1,1]
	v_pk_mul_f32 v[18:19], v[202:203], v[206:207] op_sel:[0,1] op_sel_hi:[1,1]
	v_pk_mul_f32 v[20:21], v[204:205], v[206:207] op_sel:[0,1] op_sel_hi:[1,1]
	v_add_f32_dpp v16, v16, v16 quad_perm:[1,0,3,2] row_mask:0xf bank_mask:0xf bound_ctrl:1
	v_add_f32_dpp v17, v17, v17 quad_perm:[1,0,3,2] row_mask:0xf bank_mask:0xf bound_ctrl:1
	v_pk_fma_f32 v[18:19], v[2:3], v[194:195], v[18:19]
	v_add_f32_dpp v16, v16, v16 quad_perm:[2,3,0,1] row_mask:0xf bank_mask:0xf bound_ctrl:1
	v_add_f32_dpp v17, v17, v17 quad_perm:[2,3,0,1] row_mask:0xf bank_mask:0xf bound_ctrl:1
	v_pk_fma_f32 v[20:21], v[4:5], v[196:197], v[20:21]
	v_add_f32_dpp v16, v16, v16 row_half_mirror row_mask:0xf bank_mask:0xf bound_ctrl:1
	v_add_f32_dpp v17, v17, v17 row_half_mirror row_mask:0xf bank_mask:0xf bound_ctrl:1
	s_nop 0
	v_add_f32_dpp v16, v16, v16 row_mirror row_mask:0xf bank_mask:0xf bound_ctrl:1
	v_add_f32_dpp v17, v17, v17 row_mirror row_mask:0xf bank_mask:0xf bound_ctrl:1
	v_pk_fma_f32 v[2:3], v[198:199], v[16:17], v[18:19] op_sel_hi:[1,0,1]
	v_pk_fma_f32 v[4:5], v[200:201], v[16:17], v[20:21] op_sel_hi:[1,0,1]
	v_fmac_f32_e32 v17, v210, v16
	v_fmac_f32_e32 v17, v207, v211
	ds_write2_b32 v9, v15, v17 offset0:224 offset1:240
	ds_read_b128 v[98:101], v6 offset:23040
	ds_read_b128 v[102:105], v6 offset:23056
	ds_read_b128 v[106:109], v6 offset:23072
	ds_read_b128 v[110:113], v6 offset:23088
	ds_read_b128 v[114:117], v6 offset:23104
	ds_read2st64_b32 v[206:207], v7 offset0:18 offset1:19
	ds_read_b128 v[208:211], v8 offset:144
	s_waitcnt lgkmcnt(13)
	v_pk_mul_f32 v[10:11], v[2:3], v[58:59] op_sel_hi:[0,1]
	v_pk_fma_f32 v[10:11], v[2:3], v[60:61], v[10:11] op_sel:[1,0,0] op_sel_hi:[1,1,1]
	v_pk_fma_f32 v[10:11], v[4:5], v[62:63], v[10:11] op_sel_hi:[0,1,1]
	v_pk_fma_f32 v[10:11], v[4:5], v[64:65], v[10:11] op_sel:[1,0,0] op_sel_hi:[1,1,1]
	v_pk_mul_f32 v[18:19], v[74:75], v[118:119] op_sel_hi:[1,0]
	v_pk_mul_f32 v[20:21], v[76:77], v[118:119] op_sel_hi:[1,0]
	v_add_f32_dpp v10, v10, v10 quad_perm:[1,0,3,2] row_mask:0xf bank_mask:0xf bound_ctrl:1
	v_add_f32_dpp v11, v11, v11 quad_perm:[1,0,3,2] row_mask:0xf bank_mask:0xf bound_ctrl:1
	v_pk_fma_f32 v[18:19], v[2:3], v[66:67], v[18:19]
	v_add_f32_dpp v10, v10, v10 quad_perm:[2,3,0,1] row_mask:0xf bank_mask:0xf bound_ctrl:1
	v_add_f32_dpp v11, v11, v11 quad_perm:[2,3,0,1] row_mask:0xf bank_mask:0xf bound_ctrl:1
	v_pk_fma_f32 v[20:21], v[4:5], v[68:69], v[20:21]
	v_add_f32_dpp v10, v10, v10 row_half_mirror row_mask:0xf bank_mask:0xf bound_ctrl:1
	v_add_f32_dpp v11, v11, v11 row_half_mirror row_mask:0xf bank_mask:0xf bound_ctrl:1
	s_nop 0
	v_add_f32_dpp v10, v10, v10 row_mirror row_mask:0xf bank_mask:0xf bound_ctrl:1
	v_add_f32_dpp v11, v11, v11 row_mirror row_mask:0xf bank_mask:0xf bound_ctrl:1
	v_pk_fma_f32 v[2:3], v[70:71], v[10:11], v[18:19] op_sel_hi:[1,0,1]
	v_pk_fma_f32 v[4:5], v[72:73], v[10:11], v[20:21] op_sel_hi:[1,0,1]
	v_fmac_f32_e32 v11, v120, v10
	v_fmac_f32_e32 v11, v118, v121
	ds_read_b128 v[186:189], v6 offset:24320
	ds_read_b128 v[190:193], v6 offset:24336
	ds_read_b128 v[194:197], v6 offset:24352
	ds_read_b128 v[198:201], v6 offset:24368
	ds_read_b128 v[202:205], v6 offset:24384
	s_waitcnt lgkmcnt(13)
	v_pk_mul_f32 v[12:13], v[2:3], v[78:79] op_sel_hi:[0,1]
	v_pk_fma_f32 v[12:13], v[2:3], v[80:81], v[12:13] op_sel:[1,0,0] op_sel_hi:[1,1,1]
	v_pk_fma_f32 v[12:13], v[4:5], v[82:83], v[12:13] op_sel_hi:[0,1,1]
	v_pk_fma_f32 v[12:13], v[4:5], v[84:85], v[12:13] op_sel:[1,0,0] op_sel_hi:[1,1,1]
	v_pk_mul_f32 v[18:19], v[94:95], v[118:119] op_sel:[0,1] op_sel_hi:[1,1]
	v_pk_mul_f32 v[20:21], v[96:97], v[118:119] op_sel:[0,1] op_sel_hi:[1,1]
	v_add_f32_dpp v12, v12, v12 quad_perm:[1,0,3,2] row_mask:0xf bank_mask:0xf bound_ctrl:1
	v_add_f32_dpp v13, v13, v13 quad_perm:[1,0,3,2] row_mask:0xf bank_mask:0xf bound_ctrl:1
	v_pk_fma_f32 v[18:19], v[2:3], v[86:87], v[18:19]
	v_add_f32_dpp v12, v12, v12 quad_perm:[2,3,0,1] row_mask:0xf bank_mask:0xf bound_ctrl:1
	v_add_f32_dpp v13, v13, v13 quad_perm:[2,3,0,1] row_mask:0xf bank_mask:0xf bound_ctrl:1
	v_pk_fma_f32 v[20:21], v[4:5], v[88:89], v[20:21]
	v_add_f32_dpp v12, v12, v12 row_half_mirror row_mask:0xf bank_mask:0xf bound_ctrl:1
	v_add_f32_dpp v13, v13, v13 row_half_mirror row_mask:0xf bank_mask:0xf bound_ctrl:1
	s_nop 0
	v_add_f32_dpp v12, v12, v12 row_mirror row_mask:0xf bank_mask:0xf bound_ctrl:1
	v_add_f32_dpp v13, v13, v13 row_mirror row_mask:0xf bank_mask:0xf bound_ctrl:1
	v_pk_fma_f32 v[2:3], v[90:91], v[12:13], v[18:19] op_sel_hi:[1,0,1]
	v_pk_fma_f32 v[4:5], v[92:93], v[12:13], v[20:21] op_sel_hi:[1,0,1]
	v_fmac_f32_e32 v13, v122, v12
	v_fmac_f32_e32 v13, v119, v123
	ds_write2_b32 v22, v11, v13 offset1:16
	ds_read_b128 v[58:61], v6 offset:25600
	ds_read_b128 v[62:65], v6 offset:25616
	ds_read_b128 v[66:69], v6 offset:25632
	ds_read_b128 v[70:73], v6 offset:25648
	ds_read_b128 v[74:77], v6 offset:25664
	ds_read2st64_b32 v[118:119], v7 offset0:20 offset1:21
	ds_read_b128 v[120:123], v8 offset:160
	s_waitcnt lgkmcnt(13)
	v_pk_mul_f32 v[14:15], v[2:3], v[98:99] op_sel_hi:[0,1]
	v_pk_fma_f32 v[14:15], v[2:3], v[100:101], v[14:15] op_sel:[1,0,0] op_sel_hi:[1,1,1]
	v_pk_fma_f32 v[14:15], v[4:5], v[102:103], v[14:15] op_sel_hi:[0,1,1]
	v_pk_fma_f32 v[14:15], v[4:5], v[104:105], v[14:15] op_sel:[1,0,0] op_sel_hi:[1,1,1]
	v_pk_mul_f32 v[18:19], v[114:115], v[206:207] op_sel_hi:[1,0]
	v_pk_mul_f32 v[20:21], v[116:117], v[206:207] op_sel_hi:[1,0]
	v_add_f32_dpp v14, v14, v14 quad_perm:[1,0,3,2] row_mask:0xf bank_mask:0xf bound_ctrl:1
	v_add_f32_dpp v15, v15, v15 quad_perm:[1,0,3,2] row_mask:0xf bank_mask:0xf bound_ctrl:1
	v_pk_fma_f32 v[18:19], v[2:3], v[106:107], v[18:19]
	v_add_f32_dpp v14, v14, v14 quad_perm:[2,3,0,1] row_mask:0xf bank_mask:0xf bound_ctrl:1
	v_add_f32_dpp v15, v15, v15 quad_perm:[2,3,0,1] row_mask:0xf bank_mask:0xf bound_ctrl:1
	v_pk_fma_f32 v[20:21], v[4:5], v[108:109], v[20:21]
	v_add_f32_dpp v14, v14, v14 row_half_mirror row_mask:0xf bank_mask:0xf bound_ctrl:1
	v_add_f32_dpp v15, v15, v15 row_half_mirror row_mask:0xf bank_mask:0xf bound_ctrl:1
	s_nop 0
	v_add_f32_dpp v14, v14, v14 row_mirror row_mask:0xf bank_mask:0xf bound_ctrl:1
	v_add_f32_dpp v15, v15, v15 row_mirror row_mask:0xf bank_mask:0xf bound_ctrl:1
	v_pk_fma_f32 v[2:3], v[110:111], v[14:15], v[18:19] op_sel_hi:[1,0,1]
	v_pk_fma_f32 v[4:5], v[112:113], v[14:15], v[20:21] op_sel_hi:[1,0,1]
	v_fmac_f32_e32 v15, v208, v14
	v_fmac_f32_e32 v15, v206, v209
	ds_read_b128 v[78:81], v6 offset:26880
	ds_read_b128 v[82:85], v6 offset:26896
	ds_read_b128 v[86:89], v6 offset:26912
	ds_read_b128 v[90:93], v6 offset:26928
	ds_read_b128 v[94:97], v6 offset:26944
	s_waitcnt lgkmcnt(13)
	v_pk_mul_f32 v[16:17], v[2:3], v[186:187] op_sel_hi:[0,1]
	v_pk_fma_f32 v[16:17], v[2:3], v[188:189], v[16:17] op_sel:[1,0,0] op_sel_hi:[1,1,1]
	v_pk_fma_f32 v[16:17], v[4:5], v[190:191], v[16:17] op_sel_hi:[0,1,1]
	v_pk_fma_f32 v[16:17], v[4:5], v[192:193], v[16:17] op_sel:[1,0,0] op_sel_hi:[1,1,1]
	v_pk_mul_f32 v[18:19], v[202:203], v[206:207] op_sel:[0,1] op_sel_hi:[1,1]
	v_pk_mul_f32 v[20:21], v[204:205], v[206:207] op_sel:[0,1] op_sel_hi:[1,1]
	v_add_f32_dpp v16, v16, v16 quad_perm:[1,0,3,2] row_mask:0xf bank_mask:0xf bound_ctrl:1
	v_add_f32_dpp v17, v17, v17 quad_perm:[1,0,3,2] row_mask:0xf bank_mask:0xf bound_ctrl:1
	v_pk_fma_f32 v[18:19], v[2:3], v[194:195], v[18:19]
	v_add_f32_dpp v16, v16, v16 quad_perm:[2,3,0,1] row_mask:0xf bank_mask:0xf bound_ctrl:1
	v_add_f32_dpp v17, v17, v17 quad_perm:[2,3,0,1] row_mask:0xf bank_mask:0xf bound_ctrl:1
	v_pk_fma_f32 v[20:21], v[4:5], v[196:197], v[20:21]
	v_add_f32_dpp v16, v16, v16 row_half_mirror row_mask:0xf bank_mask:0xf bound_ctrl:1
	v_add_f32_dpp v17, v17, v17 row_half_mirror row_mask:0xf bank_mask:0xf bound_ctrl:1
	s_nop 0
	v_add_f32_dpp v16, v16, v16 row_mirror row_mask:0xf bank_mask:0xf bound_ctrl:1
	v_add_f32_dpp v17, v17, v17 row_mirror row_mask:0xf bank_mask:0xf bound_ctrl:1
	v_pk_fma_f32 v[2:3], v[198:199], v[16:17], v[18:19] op_sel_hi:[1,0,1]
	v_pk_fma_f32 v[4:5], v[200:201], v[16:17], v[20:21] op_sel_hi:[1,0,1]
	v_fmac_f32_e32 v17, v210, v16
	v_fmac_f32_e32 v17, v207, v211
	ds_write2_b32 v22, v15, v17 offset0:32 offset1:48
	ds_read_b128 v[98:101], v6 offset:28160
	ds_read_b128 v[102:105], v6 offset:28176
	ds_read_b128 v[106:109], v6 offset:28192
	ds_read_b128 v[110:113], v6 offset:28208
	ds_read_b128 v[114:117], v6 offset:28224
	ds_read2st64_b32 v[206:207], v7 offset0:22 offset1:23
	ds_read_b128 v[208:211], v8 offset:176
	s_waitcnt lgkmcnt(13)
	v_pk_mul_f32 v[10:11], v[2:3], v[58:59] op_sel_hi:[0,1]
	v_pk_fma_f32 v[10:11], v[2:3], v[60:61], v[10:11] op_sel:[1,0,0] op_sel_hi:[1,1,1]
	v_pk_fma_f32 v[10:11], v[4:5], v[62:63], v[10:11] op_sel_hi:[0,1,1]
	v_pk_fma_f32 v[10:11], v[4:5], v[64:65], v[10:11] op_sel:[1,0,0] op_sel_hi:[1,1,1]
	v_pk_mul_f32 v[18:19], v[74:75], v[118:119] op_sel_hi:[1,0]
	v_pk_mul_f32 v[20:21], v[76:77], v[118:119] op_sel_hi:[1,0]
	v_add_f32_dpp v10, v10, v10 quad_perm:[1,0,3,2] row_mask:0xf bank_mask:0xf bound_ctrl:1
	v_add_f32_dpp v11, v11, v11 quad_perm:[1,0,3,2] row_mask:0xf bank_mask:0xf bound_ctrl:1
	v_pk_fma_f32 v[18:19], v[2:3], v[66:67], v[18:19]
	v_add_f32_dpp v10, v10, v10 quad_perm:[2,3,0,1] row_mask:0xf bank_mask:0xf bound_ctrl:1
	v_add_f32_dpp v11, v11, v11 quad_perm:[2,3,0,1] row_mask:0xf bank_mask:0xf bound_ctrl:1
	v_pk_fma_f32 v[20:21], v[4:5], v[68:69], v[20:21]
	v_add_f32_dpp v10, v10, v10 row_half_mirror row_mask:0xf bank_mask:0xf bound_ctrl:1
	v_add_f32_dpp v11, v11, v11 row_half_mirror row_mask:0xf bank_mask:0xf bound_ctrl:1
	s_nop 0
	v_add_f32_dpp v10, v10, v10 row_mirror row_mask:0xf bank_mask:0xf bound_ctrl:1
	v_add_f32_dpp v11, v11, v11 row_mirror row_mask:0xf bank_mask:0xf bound_ctrl:1
	v_pk_fma_f32 v[2:3], v[70:71], v[10:11], v[18:19] op_sel_hi:[1,0,1]
	v_pk_fma_f32 v[4:5], v[72:73], v[10:11], v[20:21] op_sel_hi:[1,0,1]
	v_fmac_f32_e32 v11, v120, v10
	v_fmac_f32_e32 v11, v118, v121
	ds_read_b128 v[186:189], v6 offset:29440
	ds_read_b128 v[190:193], v6 offset:29456
	ds_read_b128 v[194:197], v6 offset:29472
	ds_read_b128 v[198:201], v6 offset:29488
	ds_read_b128 v[202:205], v6 offset:29504
	s_waitcnt lgkmcnt(13)
	v_pk_mul_f32 v[12:13], v[2:3], v[78:79] op_sel_hi:[0,1]
	v_pk_fma_f32 v[12:13], v[2:3], v[80:81], v[12:13] op_sel:[1,0,0] op_sel_hi:[1,1,1]
	v_pk_fma_f32 v[12:13], v[4:5], v[82:83], v[12:13] op_sel_hi:[0,1,1]
	v_pk_fma_f32 v[12:13], v[4:5], v[84:85], v[12:13] op_sel:[1,0,0] op_sel_hi:[1,1,1]
	v_pk_mul_f32 v[18:19], v[94:95], v[118:119] op_sel:[0,1] op_sel_hi:[1,1]
	v_pk_mul_f32 v[20:21], v[96:97], v[118:119] op_sel:[0,1] op_sel_hi:[1,1]
	v_add_f32_dpp v12, v12, v12 quad_perm:[1,0,3,2] row_mask:0xf bank_mask:0xf bound_ctrl:1
	v_add_f32_dpp v13, v13, v13 quad_perm:[1,0,3,2] row_mask:0xf bank_mask:0xf bound_ctrl:1
	v_pk_fma_f32 v[18:19], v[2:3], v[86:87], v[18:19]
	v_add_f32_dpp v12, v12, v12 quad_perm:[2,3,0,1] row_mask:0xf bank_mask:0xf bound_ctrl:1
	v_add_f32_dpp v13, v13, v13 quad_perm:[2,3,0,1] row_mask:0xf bank_mask:0xf bound_ctrl:1
	v_pk_fma_f32 v[20:21], v[4:5], v[88:89], v[20:21]
	v_add_f32_dpp v12, v12, v12 row_half_mirror row_mask:0xf bank_mask:0xf bound_ctrl:1
	v_add_f32_dpp v13, v13, v13 row_half_mirror row_mask:0xf bank_mask:0xf bound_ctrl:1
	s_nop 0
	v_add_f32_dpp v12, v12, v12 row_mirror row_mask:0xf bank_mask:0xf bound_ctrl:1
	v_add_f32_dpp v13, v13, v13 row_mirror row_mask:0xf bank_mask:0xf bound_ctrl:1
	v_pk_fma_f32 v[2:3], v[90:91], v[12:13], v[18:19] op_sel_hi:[1,0,1]
	v_pk_fma_f32 v[4:5], v[92:93], v[12:13], v[20:21] op_sel_hi:[1,0,1]
	v_fmac_f32_e32 v13, v122, v12
	v_fmac_f32_e32 v13, v119, v123
	ds_write2_b32 v22, v11, v13 offset0:64 offset1:80
	ds_read_b128 v[58:61], v6 offset:30720
	ds_read_b128 v[62:65], v6 offset:30736
	ds_read_b128 v[66:69], v6 offset:30752
	ds_read_b128 v[70:73], v6 offset:30768
	ds_read_b128 v[74:77], v6 offset:30784
	ds_read2st64_b32 v[118:119], v7 offset0:24 offset1:25
	ds_read_b128 v[120:123], v8 offset:192
	s_waitcnt lgkmcnt(13)
	v_pk_mul_f32 v[14:15], v[2:3], v[98:99] op_sel_hi:[0,1]
	v_pk_fma_f32 v[14:15], v[2:3], v[100:101], v[14:15] op_sel:[1,0,0] op_sel_hi:[1,1,1]
	v_pk_fma_f32 v[14:15], v[4:5], v[102:103], v[14:15] op_sel_hi:[0,1,1]
	v_pk_fma_f32 v[14:15], v[4:5], v[104:105], v[14:15] op_sel:[1,0,0] op_sel_hi:[1,1,1]
	v_pk_mul_f32 v[18:19], v[114:115], v[206:207] op_sel_hi:[1,0]
	v_pk_mul_f32 v[20:21], v[116:117], v[206:207] op_sel_hi:[1,0]
	v_add_f32_dpp v14, v14, v14 quad_perm:[1,0,3,2] row_mask:0xf bank_mask:0xf bound_ctrl:1
	v_add_f32_dpp v15, v15, v15 quad_perm:[1,0,3,2] row_mask:0xf bank_mask:0xf bound_ctrl:1
	v_pk_fma_f32 v[18:19], v[2:3], v[106:107], v[18:19]
	v_add_f32_dpp v14, v14, v14 quad_perm:[2,3,0,1] row_mask:0xf bank_mask:0xf bound_ctrl:1
	v_add_f32_dpp v15, v15, v15 quad_perm:[2,3,0,1] row_mask:0xf bank_mask:0xf bound_ctrl:1
	v_pk_fma_f32 v[20:21], v[4:5], v[108:109], v[20:21]
	v_add_f32_dpp v14, v14, v14 row_half_mirror row_mask:0xf bank_mask:0xf bound_ctrl:1
	v_add_f32_dpp v15, v15, v15 row_half_mirror row_mask:0xf bank_mask:0xf bound_ctrl:1
	s_nop 0
	v_add_f32_dpp v14, v14, v14 row_mirror row_mask:0xf bank_mask:0xf bound_ctrl:1
	v_add_f32_dpp v15, v15, v15 row_mirror row_mask:0xf bank_mask:0xf bound_ctrl:1
	v_pk_fma_f32 v[2:3], v[110:111], v[14:15], v[18:19] op_sel_hi:[1,0,1]
	v_pk_fma_f32 v[4:5], v[112:113], v[14:15], v[20:21] op_sel_hi:[1,0,1]
	v_fmac_f32_e32 v15, v208, v14
	v_fmac_f32_e32 v15, v206, v209
	ds_read_b128 v[78:81], v6 offset:32000
	ds_read_b128 v[82:85], v6 offset:32016
	ds_read_b128 v[86:89], v6 offset:32032
	ds_read_b128 v[90:93], v6 offset:32048
	ds_read_b128 v[94:97], v6 offset:32064
	s_waitcnt lgkmcnt(13)
	v_pk_mul_f32 v[16:17], v[2:3], v[186:187] op_sel_hi:[0,1]
	v_pk_fma_f32 v[16:17], v[2:3], v[188:189], v[16:17] op_sel:[1,0,0] op_sel_hi:[1,1,1]
	v_pk_fma_f32 v[16:17], v[4:5], v[190:191], v[16:17] op_sel_hi:[0,1,1]
	v_pk_fma_f32 v[16:17], v[4:5], v[192:193], v[16:17] op_sel:[1,0,0] op_sel_hi:[1,1,1]
	v_pk_mul_f32 v[18:19], v[202:203], v[206:207] op_sel:[0,1] op_sel_hi:[1,1]
	v_pk_mul_f32 v[20:21], v[204:205], v[206:207] op_sel:[0,1] op_sel_hi:[1,1]
	v_add_f32_dpp v16, v16, v16 quad_perm:[1,0,3,2] row_mask:0xf bank_mask:0xf bound_ctrl:1
	v_add_f32_dpp v17, v17, v17 quad_perm:[1,0,3,2] row_mask:0xf bank_mask:0xf bound_ctrl:1
	v_pk_fma_f32 v[18:19], v[2:3], v[194:195], v[18:19]
	v_add_f32_dpp v16, v16, v16 quad_perm:[2,3,0,1] row_mask:0xf bank_mask:0xf bound_ctrl:1
	v_add_f32_dpp v17, v17, v17 quad_perm:[2,3,0,1] row_mask:0xf bank_mask:0xf bound_ctrl:1
	v_pk_fma_f32 v[20:21], v[4:5], v[196:197], v[20:21]
	v_add_f32_dpp v16, v16, v16 row_half_mirror row_mask:0xf bank_mask:0xf bound_ctrl:1
	v_add_f32_dpp v17, v17, v17 row_half_mirror row_mask:0xf bank_mask:0xf bound_ctrl:1
	s_nop 0
	v_add_f32_dpp v16, v16, v16 row_mirror row_mask:0xf bank_mask:0xf bound_ctrl:1
	v_add_f32_dpp v17, v17, v17 row_mirror row_mask:0xf bank_mask:0xf bound_ctrl:1
	v_pk_fma_f32 v[2:3], v[198:199], v[16:17], v[18:19] op_sel_hi:[1,0,1]
	v_pk_fma_f32 v[4:5], v[200:201], v[16:17], v[20:21] op_sel_hi:[1,0,1]
	v_fmac_f32_e32 v17, v210, v16
	v_fmac_f32_e32 v17, v207, v211
	ds_write2_b32 v22, v15, v17 offset0:96 offset1:112
	ds_read_b128 v[98:101], v6 offset:33280
	ds_read_b128 v[102:105], v6 offset:33296
	ds_read_b128 v[106:109], v6 offset:33312
	ds_read_b128 v[110:113], v6 offset:33328
	ds_read_b128 v[114:117], v6 offset:33344
	ds_read2st64_b32 v[206:207], v7 offset0:26 offset1:27
	ds_read_b128 v[208:211], v8 offset:208
	s_waitcnt lgkmcnt(13)
	v_pk_mul_f32 v[10:11], v[2:3], v[58:59] op_sel_hi:[0,1]
	v_pk_fma_f32 v[10:11], v[2:3], v[60:61], v[10:11] op_sel:[1,0,0] op_sel_hi:[1,1,1]
	v_pk_fma_f32 v[10:11], v[4:5], v[62:63], v[10:11] op_sel_hi:[0,1,1]
	v_pk_fma_f32 v[10:11], v[4:5], v[64:65], v[10:11] op_sel:[1,0,0] op_sel_hi:[1,1,1]
	v_pk_mul_f32 v[18:19], v[74:75], v[118:119] op_sel_hi:[1,0]
	v_pk_mul_f32 v[20:21], v[76:77], v[118:119] op_sel_hi:[1,0]
	v_add_f32_dpp v10, v10, v10 quad_perm:[1,0,3,2] row_mask:0xf bank_mask:0xf bound_ctrl:1
	v_add_f32_dpp v11, v11, v11 quad_perm:[1,0,3,2] row_mask:0xf bank_mask:0xf bound_ctrl:1
	v_pk_fma_f32 v[18:19], v[2:3], v[66:67], v[18:19]
	v_add_f32_dpp v10, v10, v10 quad_perm:[2,3,0,1] row_mask:0xf bank_mask:0xf bound_ctrl:1
	v_add_f32_dpp v11, v11, v11 quad_perm:[2,3,0,1] row_mask:0xf bank_mask:0xf bound_ctrl:1
	v_pk_fma_f32 v[20:21], v[4:5], v[68:69], v[20:21]
	v_add_f32_dpp v10, v10, v10 row_half_mirror row_mask:0xf bank_mask:0xf bound_ctrl:1
	v_add_f32_dpp v11, v11, v11 row_half_mirror row_mask:0xf bank_mask:0xf bound_ctrl:1
	s_nop 0
	v_add_f32_dpp v10, v10, v10 row_mirror row_mask:0xf bank_mask:0xf bound_ctrl:1
	v_add_f32_dpp v11, v11, v11 row_mirror row_mask:0xf bank_mask:0xf bound_ctrl:1
	v_pk_fma_f32 v[2:3], v[70:71], v[10:11], v[18:19] op_sel_hi:[1,0,1]
	v_pk_fma_f32 v[4:5], v[72:73], v[10:11], v[20:21] op_sel_hi:[1,0,1]
	v_fmac_f32_e32 v11, v120, v10
	v_fmac_f32_e32 v11, v118, v121
	ds_read_b128 v[186:189], v6 offset:34560
	ds_read_b128 v[190:193], v6 offset:34576
	ds_read_b128 v[194:197], v6 offset:34592
	ds_read_b128 v[198:201], v6 offset:34608
	ds_read_b128 v[202:205], v6 offset:34624
	s_waitcnt lgkmcnt(13)
	v_pk_mul_f32 v[12:13], v[2:3], v[78:79] op_sel_hi:[0,1]
	v_pk_fma_f32 v[12:13], v[2:3], v[80:81], v[12:13] op_sel:[1,0,0] op_sel_hi:[1,1,1]
	v_pk_fma_f32 v[12:13], v[4:5], v[82:83], v[12:13] op_sel_hi:[0,1,1]
	v_pk_fma_f32 v[12:13], v[4:5], v[84:85], v[12:13] op_sel:[1,0,0] op_sel_hi:[1,1,1]
	v_pk_mul_f32 v[18:19], v[94:95], v[118:119] op_sel:[0,1] op_sel_hi:[1,1]
	v_pk_mul_f32 v[20:21], v[96:97], v[118:119] op_sel:[0,1] op_sel_hi:[1,1]
	v_add_f32_dpp v12, v12, v12 quad_perm:[1,0,3,2] row_mask:0xf bank_mask:0xf bound_ctrl:1
	v_add_f32_dpp v13, v13, v13 quad_perm:[1,0,3,2] row_mask:0xf bank_mask:0xf bound_ctrl:1
	v_pk_fma_f32 v[18:19], v[2:3], v[86:87], v[18:19]
	v_add_f32_dpp v12, v12, v12 quad_perm:[2,3,0,1] row_mask:0xf bank_mask:0xf bound_ctrl:1
	v_add_f32_dpp v13, v13, v13 quad_perm:[2,3,0,1] row_mask:0xf bank_mask:0xf bound_ctrl:1
	v_pk_fma_f32 v[20:21], v[4:5], v[88:89], v[20:21]
	v_add_f32_dpp v12, v12, v12 row_half_mirror row_mask:0xf bank_mask:0xf bound_ctrl:1
	v_add_f32_dpp v13, v13, v13 row_half_mirror row_mask:0xf bank_mask:0xf bound_ctrl:1
	s_nop 0
	v_add_f32_dpp v12, v12, v12 row_mirror row_mask:0xf bank_mask:0xf bound_ctrl:1
	v_add_f32_dpp v13, v13, v13 row_mirror row_mask:0xf bank_mask:0xf bound_ctrl:1
	v_pk_fma_f32 v[2:3], v[90:91], v[12:13], v[18:19] op_sel_hi:[1,0,1]
	v_pk_fma_f32 v[4:5], v[92:93], v[12:13], v[20:21] op_sel_hi:[1,0,1]
	v_fmac_f32_e32 v13, v122, v12
	v_fmac_f32_e32 v13, v119, v123
	ds_write2_b32 v22, v11, v13 offset0:128 offset1:144
	ds_read_b128 v[58:61], v6 offset:35840
	ds_read_b128 v[62:65], v6 offset:35856
	ds_read_b128 v[66:69], v6 offset:35872
	ds_read_b128 v[70:73], v6 offset:35888
	ds_read_b128 v[74:77], v6 offset:35904
	ds_read2st64_b32 v[118:119], v7 offset0:28 offset1:29
	ds_read_b128 v[120:123], v8 offset:224
	s_waitcnt lgkmcnt(13)
	v_pk_mul_f32 v[14:15], v[2:3], v[98:99] op_sel_hi:[0,1]
	v_pk_fma_f32 v[14:15], v[2:3], v[100:101], v[14:15] op_sel:[1,0,0] op_sel_hi:[1,1,1]
	v_pk_fma_f32 v[14:15], v[4:5], v[102:103], v[14:15] op_sel_hi:[0,1,1]
	v_pk_fma_f32 v[14:15], v[4:5], v[104:105], v[14:15] op_sel:[1,0,0] op_sel_hi:[1,1,1]
	v_pk_mul_f32 v[18:19], v[114:115], v[206:207] op_sel_hi:[1,0]
	v_pk_mul_f32 v[20:21], v[116:117], v[206:207] op_sel_hi:[1,0]
	v_add_f32_dpp v14, v14, v14 quad_perm:[1,0,3,2] row_mask:0xf bank_mask:0xf bound_ctrl:1
	v_add_f32_dpp v15, v15, v15 quad_perm:[1,0,3,2] row_mask:0xf bank_mask:0xf bound_ctrl:1
	v_pk_fma_f32 v[18:19], v[2:3], v[106:107], v[18:19]
	v_add_f32_dpp v14, v14, v14 quad_perm:[2,3,0,1] row_mask:0xf bank_mask:0xf bound_ctrl:1
	v_add_f32_dpp v15, v15, v15 quad_perm:[2,3,0,1] row_mask:0xf bank_mask:0xf bound_ctrl:1
	v_pk_fma_f32 v[20:21], v[4:5], v[108:109], v[20:21]
	v_add_f32_dpp v14, v14, v14 row_half_mirror row_mask:0xf bank_mask:0xf bound_ctrl:1
	v_add_f32_dpp v15, v15, v15 row_half_mirror row_mask:0xf bank_mask:0xf bound_ctrl:1
	s_nop 0
	v_add_f32_dpp v14, v14, v14 row_mirror row_mask:0xf bank_mask:0xf bound_ctrl:1
	v_add_f32_dpp v15, v15, v15 row_mirror row_mask:0xf bank_mask:0xf bound_ctrl:1
	v_pk_fma_f32 v[2:3], v[110:111], v[14:15], v[18:19] op_sel_hi:[1,0,1]
	v_pk_fma_f32 v[4:5], v[112:113], v[14:15], v[20:21] op_sel_hi:[1,0,1]
	v_fmac_f32_e32 v15, v208, v14
	v_fmac_f32_e32 v15, v206, v209
	ds_read_b128 v[78:81], v6 offset:37120
	ds_read_b128 v[82:85], v6 offset:37136
	ds_read_b128 v[86:89], v6 offset:37152
	ds_read_b128 v[90:93], v6 offset:37168
	ds_read_b128 v[94:97], v6 offset:37184
	s_waitcnt lgkmcnt(13)
	v_pk_mul_f32 v[16:17], v[2:3], v[186:187] op_sel_hi:[0,1]
	v_pk_fma_f32 v[16:17], v[2:3], v[188:189], v[16:17] op_sel:[1,0,0] op_sel_hi:[1,1,1]
	v_pk_fma_f32 v[16:17], v[4:5], v[190:191], v[16:17] op_sel_hi:[0,1,1]
	v_pk_fma_f32 v[16:17], v[4:5], v[192:193], v[16:17] op_sel:[1,0,0] op_sel_hi:[1,1,1]
	v_pk_mul_f32 v[18:19], v[202:203], v[206:207] op_sel:[0,1] op_sel_hi:[1,1]
	v_pk_mul_f32 v[20:21], v[204:205], v[206:207] op_sel:[0,1] op_sel_hi:[1,1]
	v_add_f32_dpp v16, v16, v16 quad_perm:[1,0,3,2] row_mask:0xf bank_mask:0xf bound_ctrl:1
	v_add_f32_dpp v17, v17, v17 quad_perm:[1,0,3,2] row_mask:0xf bank_mask:0xf bound_ctrl:1
	v_pk_fma_f32 v[18:19], v[2:3], v[194:195], v[18:19]
	v_add_f32_dpp v16, v16, v16 quad_perm:[2,3,0,1] row_mask:0xf bank_mask:0xf bound_ctrl:1
	v_add_f32_dpp v17, v17, v17 quad_perm:[2,3,0,1] row_mask:0xf bank_mask:0xf bound_ctrl:1
	v_pk_fma_f32 v[20:21], v[4:5], v[196:197], v[20:21]
	v_add_f32_dpp v16, v16, v16 row_half_mirror row_mask:0xf bank_mask:0xf bound_ctrl:1
	v_add_f32_dpp v17, v17, v17 row_half_mirror row_mask:0xf bank_mask:0xf bound_ctrl:1
	s_nop 0
	v_add_f32_dpp v16, v16, v16 row_mirror row_mask:0xf bank_mask:0xf bound_ctrl:1
	v_add_f32_dpp v17, v17, v17 row_mirror row_mask:0xf bank_mask:0xf bound_ctrl:1
	v_pk_fma_f32 v[2:3], v[198:199], v[16:17], v[18:19] op_sel_hi:[1,0,1]
	v_pk_fma_f32 v[4:5], v[200:201], v[16:17], v[20:21] op_sel_hi:[1,0,1]
	v_fmac_f32_e32 v17, v210, v16
	v_fmac_f32_e32 v17, v207, v211
	ds_write2_b32 v22, v15, v17 offset0:160 offset1:176
	ds_read_b128 v[98:101], v6 offset:38400
	ds_read_b128 v[102:105], v6 offset:38416
	ds_read_b128 v[106:109], v6 offset:38432
	ds_read_b128 v[110:113], v6 offset:38448
	ds_read_b128 v[114:117], v6 offset:38464
	ds_read2st64_b32 v[206:207], v7 offset0:30 offset1:31
	ds_read_b128 v[208:211], v8 offset:240
	s_waitcnt lgkmcnt(13)
	v_pk_mul_f32 v[10:11], v[2:3], v[58:59] op_sel_hi:[0,1]
	v_pk_fma_f32 v[10:11], v[2:3], v[60:61], v[10:11] op_sel:[1,0,0] op_sel_hi:[1,1,1]
	v_pk_fma_f32 v[10:11], v[4:5], v[62:63], v[10:11] op_sel_hi:[0,1,1]
	v_pk_fma_f32 v[10:11], v[4:5], v[64:65], v[10:11] op_sel:[1,0,0] op_sel_hi:[1,1,1]
	v_pk_mul_f32 v[18:19], v[74:75], v[118:119] op_sel_hi:[1,0]
	v_pk_mul_f32 v[20:21], v[76:77], v[118:119] op_sel_hi:[1,0]
	v_add_f32_dpp v10, v10, v10 quad_perm:[1,0,3,2] row_mask:0xf bank_mask:0xf bound_ctrl:1
	v_add_f32_dpp v11, v11, v11 quad_perm:[1,0,3,2] row_mask:0xf bank_mask:0xf bound_ctrl:1
	v_pk_fma_f32 v[18:19], v[2:3], v[66:67], v[18:19]
	v_add_f32_dpp v10, v10, v10 quad_perm:[2,3,0,1] row_mask:0xf bank_mask:0xf bound_ctrl:1
	v_add_f32_dpp v11, v11, v11 quad_perm:[2,3,0,1] row_mask:0xf bank_mask:0xf bound_ctrl:1
	v_pk_fma_f32 v[20:21], v[4:5], v[68:69], v[20:21]
	v_add_f32_dpp v10, v10, v10 row_half_mirror row_mask:0xf bank_mask:0xf bound_ctrl:1
	v_add_f32_dpp v11, v11, v11 row_half_mirror row_mask:0xf bank_mask:0xf bound_ctrl:1
	s_nop 0
	v_add_f32_dpp v10, v10, v10 row_mirror row_mask:0xf bank_mask:0xf bound_ctrl:1
	v_add_f32_dpp v11, v11, v11 row_mirror row_mask:0xf bank_mask:0xf bound_ctrl:1
	v_pk_fma_f32 v[2:3], v[70:71], v[10:11], v[18:19] op_sel_hi:[1,0,1]
	v_pk_fma_f32 v[4:5], v[72:73], v[10:11], v[20:21] op_sel_hi:[1,0,1]
	v_fmac_f32_e32 v11, v120, v10
	v_fmac_f32_e32 v11, v118, v121
	ds_read_b128 v[186:189], v6 offset:39680
	ds_read_b128 v[190:193], v6 offset:39696
	ds_read_b128 v[194:197], v6 offset:39712
	ds_read_b128 v[198:201], v6 offset:39728
	ds_read_b128 v[202:205], v6 offset:39744
	s_waitcnt lgkmcnt(13)
	v_pk_mul_f32 v[12:13], v[2:3], v[78:79] op_sel_hi:[0,1]
	v_pk_fma_f32 v[12:13], v[2:3], v[80:81], v[12:13] op_sel:[1,0,0] op_sel_hi:[1,1,1]
	v_pk_fma_f32 v[12:13], v[4:5], v[82:83], v[12:13] op_sel_hi:[0,1,1]
	v_pk_fma_f32 v[12:13], v[4:5], v[84:85], v[12:13] op_sel:[1,0,0] op_sel_hi:[1,1,1]
	v_pk_mul_f32 v[18:19], v[94:95], v[118:119] op_sel:[0,1] op_sel_hi:[1,1]
	v_pk_mul_f32 v[20:21], v[96:97], v[118:119] op_sel:[0,1] op_sel_hi:[1,1]
	v_add_f32_dpp v12, v12, v12 quad_perm:[1,0,3,2] row_mask:0xf bank_mask:0xf bound_ctrl:1
	v_add_f32_dpp v13, v13, v13 quad_perm:[1,0,3,2] row_mask:0xf bank_mask:0xf bound_ctrl:1
	v_pk_fma_f32 v[18:19], v[2:3], v[86:87], v[18:19]
	v_add_f32_dpp v12, v12, v12 quad_perm:[2,3,0,1] row_mask:0xf bank_mask:0xf bound_ctrl:1
	v_add_f32_dpp v13, v13, v13 quad_perm:[2,3,0,1] row_mask:0xf bank_mask:0xf bound_ctrl:1
	v_pk_fma_f32 v[20:21], v[4:5], v[88:89], v[20:21]
	v_add_f32_dpp v12, v12, v12 row_half_mirror row_mask:0xf bank_mask:0xf bound_ctrl:1
	v_add_f32_dpp v13, v13, v13 row_half_mirror row_mask:0xf bank_mask:0xf bound_ctrl:1
	s_nop 0
	v_add_f32_dpp v12, v12, v12 row_mirror row_mask:0xf bank_mask:0xf bound_ctrl:1
	v_add_f32_dpp v13, v13, v13 row_mirror row_mask:0xf bank_mask:0xf bound_ctrl:1
	v_pk_fma_f32 v[2:3], v[90:91], v[12:13], v[18:19] op_sel_hi:[1,0,1]
	v_pk_fma_f32 v[4:5], v[92:93], v[12:13], v[20:21] op_sel_hi:[1,0,1]
	v_fmac_f32_e32 v13, v122, v12
	v_fmac_f32_e32 v13, v119, v123
	ds_write2_b32 v22, v11, v13 offset0:192 offset1:208
	s_waitcnt lgkmcnt(6)
	v_pk_mul_f32 v[14:15], v[2:3], v[98:99] op_sel_hi:[0,1]
	v_pk_fma_f32 v[14:15], v[2:3], v[100:101], v[14:15] op_sel:[1,0,0] op_sel_hi:[1,1,1]
	v_pk_fma_f32 v[14:15], v[4:5], v[102:103], v[14:15] op_sel_hi:[0,1,1]
	v_pk_fma_f32 v[14:15], v[4:5], v[104:105], v[14:15] op_sel:[1,0,0] op_sel_hi:[1,1,1]
	v_pk_mul_f32 v[18:19], v[114:115], v[206:207] op_sel_hi:[1,0]
	v_pk_mul_f32 v[20:21], v[116:117], v[206:207] op_sel_hi:[1,0]
	v_add_f32_dpp v14, v14, v14 quad_perm:[1,0,3,2] row_mask:0xf bank_mask:0xf bound_ctrl:1
	v_add_f32_dpp v15, v15, v15 quad_perm:[1,0,3,2] row_mask:0xf bank_mask:0xf bound_ctrl:1
	v_pk_fma_f32 v[18:19], v[2:3], v[106:107], v[18:19]
	v_add_f32_dpp v14, v14, v14 quad_perm:[2,3,0,1] row_mask:0xf bank_mask:0xf bound_ctrl:1
	v_add_f32_dpp v15, v15, v15 quad_perm:[2,3,0,1] row_mask:0xf bank_mask:0xf bound_ctrl:1
	v_pk_fma_f32 v[20:21], v[4:5], v[108:109], v[20:21]
	v_add_f32_dpp v14, v14, v14 row_half_mirror row_mask:0xf bank_mask:0xf bound_ctrl:1
	v_add_f32_dpp v15, v15, v15 row_half_mirror row_mask:0xf bank_mask:0xf bound_ctrl:1
	s_nop 0
	v_add_f32_dpp v14, v14, v14 row_mirror row_mask:0xf bank_mask:0xf bound_ctrl:1
	v_add_f32_dpp v15, v15, v15 row_mirror row_mask:0xf bank_mask:0xf bound_ctrl:1
	v_pk_fma_f32 v[2:3], v[110:111], v[14:15], v[18:19] op_sel_hi:[1,0,1]
	v_pk_fma_f32 v[4:5], v[112:113], v[14:15], v[20:21] op_sel_hi:[1,0,1]
	v_fmac_f32_e32 v15, v208, v14
	v_fmac_f32_e32 v15, v206, v209
	s_waitcnt lgkmcnt(1)
	v_pk_mul_f32 v[16:17], v[2:3], v[186:187] op_sel_hi:[0,1]
	v_pk_fma_f32 v[16:17], v[2:3], v[188:189], v[16:17] op_sel:[1,0,0] op_sel_hi:[1,1,1]
	v_pk_fma_f32 v[16:17], v[4:5], v[190:191], v[16:17] op_sel_hi:[0,1,1]
	v_pk_fma_f32 v[16:17], v[4:5], v[192:193], v[16:17] op_sel:[1,0,0] op_sel_hi:[1,1,1]
	v_pk_mul_f32 v[18:19], v[202:203], v[206:207] op_sel:[0,1] op_sel_hi:[1,1]
	v_pk_mul_f32 v[20:21], v[204:205], v[206:207] op_sel:[0,1] op_sel_hi:[1,1]
	v_add_f32_dpp v16, v16, v16 quad_perm:[1,0,3,2] row_mask:0xf bank_mask:0xf bound_ctrl:1
	v_add_f32_dpp v17, v17, v17 quad_perm:[1,0,3,2] row_mask:0xf bank_mask:0xf bound_ctrl:1
	v_pk_fma_f32 v[18:19], v[2:3], v[194:195], v[18:19]
	v_add_f32_dpp v16, v16, v16 quad_perm:[2,3,0,1] row_mask:0xf bank_mask:0xf bound_ctrl:1
	v_add_f32_dpp v17, v17, v17 quad_perm:[2,3,0,1] row_mask:0xf bank_mask:0xf bound_ctrl:1
	v_pk_fma_f32 v[20:21], v[4:5], v[196:197], v[20:21]
	v_add_f32_dpp v16, v16, v16 row_half_mirror row_mask:0xf bank_mask:0xf bound_ctrl:1
	v_add_f32_dpp v17, v17, v17 row_half_mirror row_mask:0xf bank_mask:0xf bound_ctrl:1
	s_nop 0
	v_add_f32_dpp v16, v16, v16 row_mirror row_mask:0xf bank_mask:0xf bound_ctrl:1
	v_add_f32_dpp v17, v17, v17 row_mirror row_mask:0xf bank_mask:0xf bound_ctrl:1
	v_pk_fma_f32 v[2:3], v[198:199], v[16:17], v[18:19] op_sel_hi:[1,0,1]
	v_pk_fma_f32 v[4:5], v[200:201], v[16:17], v[20:21] op_sel_hi:[1,0,1]
	v_fmac_f32_e32 v17, v210, v16
	v_fmac_f32_e32 v17, v207, v211
	ds_write2_b32 v22, v15, v17 offset0:224 offset1:240
	s_add_i32 s0, s0, 1
	s_cmpk_lg_i32 s0, 0x80
	s_waitcnt lgkmcnt(0)
	s_barrier
	s_cbranch_scc1 .LBB0_726

.LBB0_765:
	s_or_b64 exec, exec, s[8:9]
	s_cmp_eq_u32 s62, 0x10000
	s_cbranch_scc1 .LBB0_777
	s_cmpk_lt_u32 s63, 0x7f
	s_cselect_b64 s[44:45], -1, 0
	s_cmpk_gt_u32 s63, 0x7e
	v_lshl_add_u64 v[134:135], s[66:67], 0, v[82:83]
	v_lshl_add_u64 v[132:133], s[66:67], 0, v[80:81]
	v_mov_b64_e32 v[130:131], v[120:121]
	v_mov_b64_e32 v[128:129], v[122:123]
	v_mov_b64_e32 v[126:127], v[106:107]
	v_mov_b64_e32 v[118:119], v[102:103]
	v_mov_b64_e32 v[124:125], v[108:109]
	v_mov_b64_e32 v[114:115], v[104:105]
	v_mov_b64_e32 v[116:117], v[110:111]
	v_mov_b64_e32 v[112:113], v[100:101]
	s_cbranch_scc1 .LBB0_768
	v_add_co_u32_e32 v114, vcc, 0xd061000, v134
	s_nop 1
	v_addc_co_u32_e32 v115, vcc, 0, v135, vcc
	v_add_co_u32_e32 v116, vcc, 0xd062000, v134
	s_nop 1
	v_addc_co_u32_e32 v117, vcc, 0, v135, vcc
	v_add_co_u32_e32 v124, vcc, 0xd05e000, v134
	s_nop 1
	v_addc_co_u32_e32 v125, vcc, 0, v135, vcc
	v_add_co_u32_e32 v126, vcc, 0xd05f000, v134
	global_load_dwordx2 v[112:113], v[114:115], off offset:1056
	s_nop 0
	global_load_dwordx2 v[114:115], v[114:115], off offset:3104
	s_nop 0
	global_load_dwordx2 v[118:119], v[116:117], off offset:1056
	s_nop 0
	global_load_dwordx2 v[116:117], v[124:125], off offset:1056
	v_addc_co_u32_e32 v127, vcc, 0, v135, vcc
	v_add_co_u32_e32 v128, vcc, 0x19010000, v132
	s_nop 1
	v_addc_co_u32_e32 v129, vcc, 0, v133, vcc
	v_add_co_u32_e32 v130, vcc, 0x1b010000, v132
	s_nop 1
	v_addc_co_u32_e32 v131, vcc, 0, v133, vcc
	global_load_dwordx2 v[124:125], v[124:125], off offset:3104
	s_nop 0
	global_load_dwordx2 v[126:127], v[126:127], off offset:1056
	s_nop 0
	global_load_dwordx2 v[128:129], v[128:129], off
	s_nop 0
	global_load_dwordx2 v[130:131], v[130:131], off
	v_add_co_u32_e32 v188, vcc, 0xd091000, v134
	s_nop 1
	v_addc_co_u32_e32 v189, vcc, 0, v135, vcc
	v_add_co_u32_e32 v190, vcc, 0xd092000, v134
	s_nop 1
	v_addc_co_u32_e32 v191, vcc, 0, v135, vcc
	v_add_co_u32_e32 v194, vcc, 0xd08e000, v134
	s_nop 1
	v_addc_co_u32_e32 v195, vcc, 0, v135, vcc
	v_add_co_u32_e32 v196, vcc, 0xd08f000, v134
	global_load_dwordx2 v[186:187], v[188:189], off offset:1056
	s_nop 0
	global_load_dwordx2 v[188:189], v[188:189], off offset:3104
	s_nop 0
	global_load_dwordx2 v[192:193], v[190:191], off offset:1056
	s_nop 0
	global_load_dwordx2 v[190:191], v[194:195], off offset:1056
	v_addc_co_u32_e32 v197, vcc, 0, v135, vcc
	v_add_co_u32_e32 v198, vcc, 0x19018000, v132
	s_nop 1
	v_addc_co_u32_e32 v199, vcc, 0, v133, vcc
	v_add_co_u32_e32 v200, vcc, 0x1b018000, v132
	s_nop 1
	v_addc_co_u32_e32 v201, vcc, 0, v133, vcc
	global_load_dwordx2 v[194:195], v[194:195], off offset:3104
	s_nop 0
	global_load_dwordx2 v[196:197], v[196:197], off offset:1056
	s_nop 0
	global_load_dwordx2 v[198:199], v[198:199], off
	s_nop 0
	global_load_dwordx2 v[200:201], v[200:201], off

.LBB0_771:
	s_or_b64 exec, exec, s[0:1]
.LBB0_773:
	v_lshlrev_b32_e32 v132, 16, v86
	v_and_b32_e32 v133, 0xffff0000, v86
	v_lshlrev_b32_e32 v134, 16, v98
	v_and_b32_e32 v135, 0xffff0000, v98
	v_lshlrev_b32_e32 v157, 16, v97
	v_and_b32_e32 v86, 0xffff0000, v97
	v_lshlrev_b32_e32 v154, 16, v96
	v_and_b32_e32 v155, 0xffff0000, v96
	v_lshlrev_b32_e32 v96, 16, v94
	v_and_b32_e32 v97, 0xffff0000, v94
	v_lshlrev_b32_e32 v98, 16, v95
	v_and_b32_e32 v153, 0xffff0000, v95
	v_lshlrev_b32_e32 v94, 16, v88
	v_and_b32_e32 v95, 0xffff0000, v88
	v_lshlrev_b32_e32 v88, 16, v90
	v_lshlrev_b32_e32 v56, 16, v87
	v_lshlrev_b32_e32 v16, 16, v99
	v_lshlrev_b32_e32 v158, 16, v92
	v_and_b32_e32 v159, 0xffff0000, v92
	v_lshlrev_b32_e32 v160, 16, v89
	v_and_b32_e32 v161, 0xffff0000, v89
	v_and_b32_e32 v89, 0xffff0000, v90
	v_lshlrev_b32_e32 v164, 16, v84
	v_and_b32_e32 v166, 0xffff0000, v84
	v_lshlrev_b32_e32 v178, 16, v85
	v_and_b32_e32 v84, 0xffff0000, v85
	v_mul_f32_e32 v85, 0xbfb8aa3b, v88
	v_lshlrev_b32_e32 v156, 16, v91
	v_and_b32_e32 v165, 0xffff0000, v91
	v_pk_add_f32 v[90:91], v[158:159], v[94:95] neg_lo:[0,1] neg_hi:[0,1]
	v_exp_f32_e32 v88, v85
	v_mul_f32_e32 v85, 0xbfb8aa3b, v89
	v_sub_f32_e32 v158, v16, v56
	v_sub_f32_e32 v16, v98, v157
	v_exp_f32_e32 v89, v85
	v_fmac_f32_e32 v157, v24, v16
	v_mul_f32_e32 v16, 0xbfb8aa3b, v156
	v_mul_f32_e32 v85, 0xbfb8aa3b, v165
	v_lshlrev_b32_e32 v162, 16, v93
	v_and_b32_e32 v163, 0xffff0000, v93
	v_pk_fma_f32 v[92:93], v[18:19], v[90:91], v[94:95]
	v_exp_f32_e32 v90, v16
	v_sub_f32_e32 v16, v153, v86
	v_exp_f32_e32 v91, v85
	v_add_f32_e32 v85, -1.0, v178
	v_and_b32_e32 v167, 0xffff0000, v87
	v_pk_add_f32 v[168:169], v[96:97], v[154:155] neg_lo:[0,1] neg_hi:[0,1]
	v_pk_add_f32 v[94:95], v[162:163], v[160:161] neg_lo:[0,1] neg_hi:[0,1]
	v_pk_add_f32 v[96:97], v[134:135], v[132:133] neg_lo:[0,1] neg_hi:[0,1]
	v_mul_f32_e32 v87, v32, v85
	v_fmac_f32_e32 v86, v25, v16
	v_pk_fma_f32 v[94:95], v[20:21], v[94:95], v[160:161]
	v_pk_fma_f32 v[134:135], v[14:15], v[96:97], v[132:133]
	v_pk_mul_f32 v[160:161], v[76:77], v[86:87]
	v_pk_add_f32 v[132:133], v[76:77], v[86:87]
	v_mul_f32_e32 v163, v28, v157
	v_mov_b32_e32 v161, v133
	v_pk_fma_f32 v[132:133], v[22:23], v[168:169], v[154:155]
	v_mov_b32_e32 v162, v160
	v_pk_mul_f32 v[154:155], v[26:27], v[132:133]
	v_pk_mul_f32 v[172:173], v[162:163], v[162:163]
	v_pk_mul_f32 v[168:169], v[154:155], v[154:155]
	v_pk_mov_b32 v[174:175], v[166:167], v[166:167] op_sel:[1,0]
	v_add_f32_e32 v87, v168, v169
	v_add_f32_e32 v87, v173, v87
	v_add_f32_e32 v87, v172, v87
	v_mov_b32_e32 v165, v175
	v_pk_add_f32 v[176:177], v[164:165], -1.0 op_sel_hi:[1,0]
	v_add_f32_dpp v87, v87, v87 quad_perm:[1,0,3,2] row_mask:0xf bank_mask:0xf bound_ctrl:1
	v_and_b32_e32 v99, 0xffff0000, v99
	v_pk_fma_f32 v[176:177], v[30:31], v[176:177], 1.0 op_sel_hi:[1,1,0]
	v_add_f32_dpp v87, v87, v87 quad_perm:[2,3,0,1] row_mask:0xf bank_mask:0xf bound_ctrl:1
	v_add_f32_e32 v159, -1.0, v84
	v_pk_mul_f32 v[132:133], v[176:177], v[132:133]
	v_add_f32_dpp v87, v87, v87 row_half_mirror row_mask:0xf bank_mask:0xf bound_ctrl:1
	v_mov_b32_e32 v16, v135
	v_pk_fma_f32 v[158:159], v[74:75], v[158:159], v[56:57]
	v_add_f32_dpp v87, v87, v87 row_mirror row_mask:0xf bank_mask:0xf bound_ctrl:1
	v_max_f32_e32 v87, 0x179abe15, v87
	v_rsq_f32_e32 v156, v87
	v_fma_f32 v175, v132, v134, 0
	v_mov_b32_e32 v176, v17
	v_mov_b32_e32 v177, v133
	v_pk_mul_f32 v[168:169], v[154:155], v[156:157] op_sel_hi:[1,0]
	v_mov_b32_e32 v165, v167
	v_mov_b32_e32 v98, v169
	v_mul_f32_e32 v154, v168, v164
	v_pk_mul_f32 v[172:173], v[98:99], v[166:167]
	v_pk_add_f32 v[98:99], v[98:99], v[166:167] neg_lo:[0,1] neg_hi:[0,1]
	v_fma_f32 v164, v134, v154, 0
	v_mov_b32_e32 v173, v99
	v_mov_b32_e32 v98, v99
	v_mov_b32_e32 v99, v135
	v_mov_b32_e32 v85, v158
	v_mul_f32_e32 v56, v132, v134
	v_pk_fma_f32 v[164:165], v[16:17], v[172:173], v[164:165]
	v_pk_fma_f32 v[166:167], v[176:177], v[98:99], v[174:175]
	v_pk_mul_f32 v[174:175], v[160:161], v[156:157]
	v_mul_f32_e64 v160, v163, -v156
	v_pk_mul_f32 v[96:97], v[88:89], v[134:135]
	v_fma_f32 v56, v10, v56, 0
	v_pk_mul_f32 v[134:135], v[132:133], v[134:135]
	v_mul_f32_e64 v156, -v160, v178
	v_pk_mul_f32 v[162:163], v[174:175], v[84:85]
	v_mov_b32_e32 v157, v86
	v_mov_b32_e32 v86, v158
	v_mov_b32_e32 v87, v165
	v_fmac_f32_e32 v56, v11, v135
	v_pk_mul_f32 v[134:135], v[158:159], v[156:157]
	v_pk_mul_f32 v[98:99], v[90:91], v[86:87]
	v_pk_mul_f32 v[86:87], v[166:167], v[162:163]
	v_pk_fma_f32 v[84:85], v[174:175], v[84:85], v[166:167]
	v_fmac_f32_e32 v56, v12, v163
	v_mov_b32_e32 v87, v85
	v_pk_fma_f32 v[84:85], v[158:159], v[156:157], v[164:165]
	v_pk_mul_f32 v[158:159], v[134:135], v[164:165]
	v_xor_b32_e32 v161, 0x80000000, v174
	v_mov_b32_e32 v85, v159
	v_pk_add_f32 v[84:85], v[84:85], v[86:87]
	v_fmac_f32_e32 v56, v13, v159
	v_xor_b32_e32 v159, 0x80000000, v169
	v_mov_b32_dpp v86, v84 quad_perm:[1,0,3,2] row_mask:0xf bank_mask:0xf bound_ctrl:1
	v_mov_b32_dpp v87, v85 quad_perm:[1,0,3,2] row_mask:0xf bank_mask:0xf bound_ctrl:1
	v_pk_add_f32 v[84:85], v[84:85], v[86:87]
	v_add_f32_dpp v16, v56, v56 quad_perm:[1,0,3,2] row_mask:0xf bank_mask:0xf bound_ctrl:1
	v_xor_b32_e32 v158, 0x80000000, v168
	v_mov_b32_dpp v86, v84 quad_perm:[2,3,0,1] row_mask:0xf bank_mask:0xf bound_ctrl:1
	v_mov_b32_dpp v87, v85 quad_perm:[2,3,0,1] row_mask:0xf bank_mask:0xf bound_ctrl:1
	v_pk_add_f32 v[84:85], v[84:85], v[86:87]
	v_add_f32_dpp v16, v16, v16 quad_perm:[2,3,0,1] row_mask:0xf bank_mask:0xf bound_ctrl:1
	v_mov_b32_e32 v155, v172
	v_mov_b32_dpp v86, v84 row_half_mirror row_mask:0xf bank_mask:0xf bound_ctrl:1
	v_mov_b32_dpp v87, v85 row_half_mirror row_mask:0xf bank_mask:0xf bound_ctrl:1
	v_pk_add_f32 v[84:85], v[84:85], v[86:87]
	v_add_f32_dpp v16, v16, v16 row_half_mirror row_mask:0xf bank_mask:0xf bound_ctrl:1
	v_mov_b32_e32 v157, v162
	v_mov_b32_dpp v86, v84 row_mirror row_mask:0xf bank_mask:0xf bound_ctrl:1
	v_mov_b32_dpp v87, v85 row_mirror row_mask:0xf bank_mask:0xf bound_ctrl:1
	v_mov_b32_dpp v56, v16 row_mirror row_mask:0xf bank_mask:0xf bound_ctrl:1
	v_mov_b32_e32 v134, v175
	v_add_u32_e32 v0, v0, v148
	v_add_u32_e32 v253, 0x5000, v69
	ds_write2_b32 v253, v158, v96 offset1:1
	ds_write2_b32 v253, v159, v97 offset0:2 offset1:3
	ds_write2_b32 v253, v160, v98 offset0:4 offset1:5
	ds_write2_b32 v253, v161, v99 offset0:6 offset1:7
	ds_write_b128 v69, v[88:91] offset:20512
	ds_write_b128 v69, v[154:157] offset:20528
	ds_write_b128 v69, v[132:135] offset:20544
	ds_write_b128 v0, v[92:95]
	s_and_saveexec_b64 s[0:1], s[6:7]
	s_cbranch_execz .LBB0_776
	v_add_u32_e32 v0, s46, v149
	v_pk_add_f32 v[84:85], v[84:85], v[86:87]
	s_and_b64 vcc, exec, s[8:9]
	ds_write_b64 v0, v[84:85]
	s_cbranch_vccnz .LBB0_776
	v_lshl_add_u64 v[84:85], s[66:67], 0, v[78:79]
	v_add_co_u32_e32 v84, vcc, 0x1f000000, v84
	v_add_f32_e32 v0, v16, v56
	s_nop 0
	v_addc_co_u32_e32 v85, vcc, 0, v85, vcc
	global_store_dword v[84:85], v0, off offset:1024

.LBB0_783:
	s_mov_b64 s[0:1], 0x800
	v_lshl_add_u64 v[78:79], v[78:79], 0, s[0:1]
	s_mov_b64 s[0:1], 0x10000
	s_add_i32 s63, s63, 1
	s_addk_i32 s62, 0x200
	s_add_i32 s16, s16, 32
	v_lshl_add_u64 v[80:81], v[80:81], 0, s[0:1]
	s_mov_b64 s[0:1], 0x60000
	s_cmp_eq_u32 s62, 0x10200
	v_lshl_add_u64 v[82:83], v[82:83], 0, s[0:1]
	s_waitcnt lgkmcnt(0)
	s_barrier
	s_cbranch_scc1 .LBB0_785
	s_waitcnt vmcnt(0)
	v_mov_b64_e32 v[84:85], v[200:201]
	v_mov_b64_e32 v[90:91], v[198:199]
	v_mov_b64_e32 v[92:93], v[196:197]
	v_mov_b64_e32 v[88:89], v[192:193]
	v_mov_b64_e32 v[94:95], v[194:195]
	v_mov_b64_e32 v[96:97], v[188:189]
	v_mov_b64_e32 v[98:99], v[190:191]
	v_mov_b64_e32 v[86:87], v[186:187]
	v_mov_b64_e32 v[120:121], v[130:131]
	v_mov_b64_e32 v[122:123], v[128:129]
	v_mov_b64_e32 v[106:107], v[126:127]
	v_mov_b64_e32 v[102:103], v[118:119]
	v_mov_b64_e32 v[108:109], v[124:125]
	v_mov_b64_e32 v[104:105], v[114:115]
	v_mov_b64_e32 v[110:111], v[116:117]
	v_mov_b64_e32 v[100:101], v[112:113]
	s_branch .LBB0_731
